# GEMM K-loops: pointer/counter SALU and exit compare moved in front of the loop-back barrier (on top of attention rotation + prio + counted waits)
# baseline (speedup 1.0000x reference)
.LBB0_266:
	ds_read_b128 v[152:155], v166
	ds_read_b128 v[156:159], v166 offset:1024
	ds_read_b128 v[172:175], v166 offset:2048
	ds_read_b128 v[176:179], v166 offset:3072
	ds_read_b128 v[180:183], v167
	ds_read_b128 v[184:187], v167 offset:1024
	ds_read_b128 v[188:191], v167 offset:2048
	ds_read_b128 v[192:195], v167 offset:3072
	s_add_u32 s62, s8, 0xfff80080
	s_addc_u32 s63, s9, -1
	s_cmp_eq_u32 s74, 28
	s_cselect_b32 s65, s11, s63
	s_cselect_b32 s64, s12, s62
	s_cselect_b32 s63, s13, s61
	s_cselect_b32 s62, s45, s49
	v_lshl_add_u64 v[228:229], s[8:9], 0, v[142:143]
	s_add_i32 m0, s79, 0xc000
	ds_read_b128 v[196:199], v168
	ds_read_b128 v[200:203], v168 offset:1024
	ds_read_b128 v[204:207], v168 offset:2048
	ds_read_b128 v[208:211], v168 offset:3072
	ds_read_b128 v[212:215], v168 offset:4096
	ds_read_b128 v[216:219], v168 offset:5120
	ds_read_b128 v[220:223], v168 offset:6144
	ds_read_b128 v[224:227], v168 offset:7168
	global_load_lds_dwordx4 v[228:229], off
	v_lshl_add_u64 v[228:229], s[8:9], 0, v[144:145]
	s_add_i32 m0, s79, 0xe000
	s_nop 0
	global_load_lds_dwordx4 v[228:229], off
	s_waitcnt vmcnt(8)
	s_waitcnt lgkmcnt(0)
	s_barrier
	s_setprio 1
	s_waitcnt lgkmcnt(0)
	v_mfma_f32_16x16x32_bf16 v[126:129], v[152:155], v[196:199], v[126:129]
	v_mfma_f32_16x16x32_bf16 v[122:125], v[172:175], v[196:199], v[122:125]
	v_mfma_f32_16x16x32_bf16 v[110:113], v[152:155], v[204:207], v[110:113]
	v_mfma_f32_16x16x32_bf16 v[106:109], v[172:175], v[204:207], v[106:109]
	v_mfma_f32_16x16x32_bf16 v[94:97], v[152:155], v[212:215], v[94:97]
	v_mfma_f32_16x16x32_bf16 v[90:93], v[172:175], v[212:215], v[90:93]
	v_mfma_f32_16x16x32_bf16 v[78:81], v[152:155], v[220:223], v[78:81]
	v_mfma_f32_16x16x32_bf16 v[74:77], v[172:175], v[220:223], v[74:77]
	v_mfma_f32_16x16x32_bf16 v[126:129], v[156:159], v[200:203], v[126:129]
	v_mfma_f32_16x16x32_bf16 v[122:125], v[176:179], v[200:203], v[122:125]
	v_mfma_f32_16x16x32_bf16 v[110:113], v[156:159], v[208:211], v[110:113]
	v_mfma_f32_16x16x32_bf16 v[106:109], v[176:179], v[208:211], v[106:109]
	v_mfma_f32_16x16x32_bf16 v[94:97], v[156:159], v[216:219], v[94:97]
	v_mfma_f32_16x16x32_bf16 v[90:93], v[176:179], v[216:219], v[90:93]
	v_mfma_f32_16x16x32_bf16 v[78:81], v[156:159], v[224:227], v[78:81]
	v_mfma_f32_16x16x32_bf16 v[74:77], v[176:179], v[224:227], v[74:77]
	s_setprio 0
	s_setprio 1
	v_mfma_f32_16x16x32_bf16 v[118:121], v[180:183], v[196:199], v[118:121]
	v_mfma_f32_16x16x32_bf16 v[114:117], v[188:191], v[196:199], v[114:117]
	v_mfma_f32_16x16x32_bf16 v[102:105], v[180:183], v[204:207], v[102:105]
	v_mfma_f32_16x16x32_bf16 v[98:101], v[188:191], v[204:207], v[98:101]
	v_mfma_f32_16x16x32_bf16 v[86:89], v[180:183], v[212:215], v[86:89]
	v_mfma_f32_16x16x32_bf16 v[82:85], v[188:191], v[212:215], v[82:85]
	v_mfma_f32_16x16x32_bf16 v[70:73], v[180:183], v[220:223], v[70:73]
	v_mfma_f32_16x16x32_bf16 v[66:69], v[188:191], v[220:223], v[66:69]
	v_mfma_f32_16x16x32_bf16 v[118:121], v[184:187], v[200:203], v[118:121]
	v_mfma_f32_16x16x32_bf16 v[114:117], v[192:195], v[200:203], v[114:117]
	v_mfma_f32_16x16x32_bf16 v[102:105], v[184:187], v[208:211], v[102:105]
	v_mfma_f32_16x16x32_bf16 v[98:101], v[192:195], v[208:211], v[98:101]
	v_mfma_f32_16x16x32_bf16 v[86:89], v[184:187], v[216:219], v[86:89]
	v_mfma_f32_16x16x32_bf16 v[82:85], v[192:195], v[216:219], v[82:85]
	v_mfma_f32_16x16x32_bf16 v[70:73], v[184:187], v[224:227], v[70:73]
	v_mfma_f32_16x16x32_bf16 v[66:69], v[192:195], v[224:227], v[66:69]
	s_setprio 0
	s_barrier
	s_add_i32 s72, s93, s78
	v_lshl_add_u64 v[228:229], s[62:63], 0, v[134:135]
	s_mov_b32 m0, s72
	ds_read_b128 v[196:199], v168 offset:16384
	ds_read_b128 v[200:203], v168 offset:17408
	ds_read_b128 v[204:207], v168 offset:18432
	ds_read_b128 v[208:211], v168 offset:19456
	ds_read_b128 v[212:215], v168 offset:20480
	ds_read_b128 v[216:219], v168 offset:21504
	ds_read_b128 v[220:223], v168 offset:22528
	ds_read_b128 v[224:227], v168 offset:23552
	global_load_lds_dwordx4 v[228:229], off
	s_add_i32 m0, s72, 0x2000
	s_add_u32 s96, s62, 0x80000
	v_lshl_add_u64 v[230:231], s[62:63], 0, v[138:139]
	s_addc_u32 s97, s63, 0
	s_add_i32 s72, s94, s78
	global_load_lds_dwordx4 v[230:231], off
	v_lshl_add_u64 v[232:233], s[96:97], 0, v[134:135]
	s_mov_b32 m0, s72
	v_lshl_add_u64 v[234:235], s[64:65], 0, v[136:137]
	global_load_lds_dwordx4 v[232:233], off
	v_lshl_add_u64 v[232:233], s[96:97], 0, v[138:139]
	s_add_i32 m0, s72, 0x2000
	s_nop 0
	global_load_lds_dwordx4 v[232:233], off
	v_lshl_add_u64 v[232:233], s[64:65], 0, v[132:133]
	s_mov_b32 m0, s79
	s_nop 0
	global_load_lds_dwordx4 v[232:233], off
	s_mov_b32 m0, s80
	s_nop 0
	global_load_lds_dwordx4 v[234:235], off
	s_waitcnt vmcnt(8)
	s_waitcnt lgkmcnt(0)
	s_barrier
	s_setprio 1
	s_waitcnt lgkmcnt(0)
	v_mfma_f32_16x16x32_bf16 v[62:65], v[152:155], v[196:199], v[62:65]
	v_mfma_f32_16x16x32_bf16 v[58:61], v[172:175], v[196:199], v[58:61]
	v_mfma_f32_16x16x32_bf16 v[46:49], v[152:155], v[204:207], v[46:49]
	v_mfma_f32_16x16x32_bf16 v[42:45], v[172:175], v[204:207], v[42:45]
	v_mfma_f32_16x16x32_bf16 v[30:33], v[152:155], v[212:215], v[30:33]
	v_mfma_f32_16x16x32_bf16 v[26:29], v[172:175], v[212:215], v[26:29]
	v_mfma_f32_16x16x32_bf16 v[14:17], v[152:155], v[220:223], v[14:17]
	v_mfma_f32_16x16x32_bf16 v[10:13], v[172:175], v[220:223], v[10:13]
	v_mfma_f32_16x16x32_bf16 v[62:65], v[156:159], v[200:203], v[62:65]
	v_mfma_f32_16x16x32_bf16 v[58:61], v[176:179], v[200:203], v[58:61]
	v_mfma_f32_16x16x32_bf16 v[46:49], v[156:159], v[208:211], v[46:49]
	v_mfma_f32_16x16x32_bf16 v[42:45], v[176:179], v[208:211], v[42:45]
	v_mfma_f32_16x16x32_bf16 v[30:33], v[156:159], v[216:219], v[30:33]
	v_mfma_f32_16x16x32_bf16 v[26:29], v[176:179], v[216:219], v[26:29]
	v_mfma_f32_16x16x32_bf16 v[14:17], v[156:159], v[224:227], v[14:17]
	v_mfma_f32_16x16x32_bf16 v[10:13], v[176:179], v[224:227], v[10:13]
	s_setprio 0
	s_setprio 1
	v_mfma_f32_16x16x32_bf16 v[54:57], v[180:183], v[196:199], v[54:57]
	v_mfma_f32_16x16x32_bf16 v[50:53], v[188:191], v[196:199], v[50:53]
	v_mfma_f32_16x16x32_bf16 v[38:41], v[180:183], v[204:207], v[38:41]
	v_mfma_f32_16x16x32_bf16 v[34:37], v[188:191], v[204:207], v[34:37]
	v_mfma_f32_16x16x32_bf16 v[22:25], v[180:183], v[212:215], v[22:25]
	v_mfma_f32_16x16x32_bf16 v[18:21], v[188:191], v[212:215], v[18:21]
	v_mfma_f32_16x16x32_bf16 v[6:9], v[180:183], v[220:223], v[6:9]
	v_mfma_f32_16x16x32_bf16 v[2:5], v[188:191], v[220:223], v[2:5]
	v_mfma_f32_16x16x32_bf16 v[54:57], v[184:187], v[200:203], v[54:57]
	v_mfma_f32_16x16x32_bf16 v[50:53], v[192:195], v[200:203], v[50:53]
	v_mfma_f32_16x16x32_bf16 v[38:41], v[184:187], v[208:211], v[38:41]
	v_mfma_f32_16x16x32_bf16 v[34:37], v[192:195], v[208:211], v[34:37]
	v_mfma_f32_16x16x32_bf16 v[22:25], v[184:187], v[216:219], v[22:25]
	v_mfma_f32_16x16x32_bf16 v[18:21], v[192:195], v[216:219], v[18:21]
	v_mfma_f32_16x16x32_bf16 v[6:9], v[184:187], v[224:227], v[6:9]
	v_mfma_f32_16x16x32_bf16 v[2:5], v[192:195], v[224:227], v[2:5]
	s_setprio 0
	s_barrier
	s_add_i32 s72, 0, 0x18000
	v_add_u32_e32 v171, s72, v160
	s_add_i32 s73, 0, 0x1c000
	ds_read_b128 v[152:155], v171
	ds_read_b128 v[156:159], v171 offset:1024
	ds_read_b128 v[172:175], v171 offset:2048
	ds_read_b128 v[176:179], v171 offset:3072
	v_add_u32_e32 v171, s73, v160
	ds_read_b128 v[180:183], v171
	ds_read_b128 v[184:187], v171 offset:1024
	ds_read_b128 v[188:191], v171 offset:2048
	ds_read_b128 v[192:195], v171 offset:3072
	s_add_u32 s64, s64, 0x80000
	s_addc_u32 s65, s65, 0
	s_mov_b32 m0, s81
	v_lshl_add_u64 v[236:237], s[64:65], 0, v[132:133]
	ds_read_b128 v[196:199], v168 offset:32768
	ds_read_b128 v[200:203], v168 offset:33792
	ds_read_b128 v[204:207], v168 offset:34816
	ds_read_b128 v[208:211], v168 offset:35840
	ds_read_b128 v[212:215], v168 offset:36864
	ds_read_b128 v[216:219], v168 offset:37888
	ds_read_b128 v[220:223], v168 offset:38912
	ds_read_b128 v[224:227], v168 offset:39936
	global_load_lds_dwordx4 v[236:237], off
	v_lshl_add_u64 v[236:237], s[64:65], 0, v[136:137]
	s_mov_b32 m0, s82
	s_nop 0
	global_load_lds_dwordx4 v[236:237], off
	s_waitcnt vmcnt(8)
	s_waitcnt lgkmcnt(0)
	s_barrier
	s_setprio 1
	s_waitcnt lgkmcnt(0)
	v_mfma_f32_16x16x32_bf16 v[126:129], v[152:155], v[196:199], v[126:129]
	v_mfma_f32_16x16x32_bf16 v[122:125], v[172:175], v[196:199], v[122:125]
	v_mfma_f32_16x16x32_bf16 v[110:113], v[152:155], v[204:207], v[110:113]
	v_mfma_f32_16x16x32_bf16 v[106:109], v[172:175], v[204:207], v[106:109]
	v_mfma_f32_16x16x32_bf16 v[94:97], v[152:155], v[212:215], v[94:97]
	v_mfma_f32_16x16x32_bf16 v[90:93], v[172:175], v[212:215], v[90:93]
	v_mfma_f32_16x16x32_bf16 v[78:81], v[152:155], v[220:223], v[78:81]
	v_mfma_f32_16x16x32_bf16 v[74:77], v[172:175], v[220:223], v[74:77]
	v_mfma_f32_16x16x32_bf16 v[126:129], v[156:159], v[200:203], v[126:129]
	v_mfma_f32_16x16x32_bf16 v[122:125], v[176:179], v[200:203], v[122:125]
	v_mfma_f32_16x16x32_bf16 v[110:113], v[156:159], v[208:211], v[110:113]
	v_mfma_f32_16x16x32_bf16 v[106:109], v[176:179], v[208:211], v[106:109]
	v_mfma_f32_16x16x32_bf16 v[94:97], v[156:159], v[216:219], v[94:97]
	v_mfma_f32_16x16x32_bf16 v[90:93], v[176:179], v[216:219], v[90:93]
	v_mfma_f32_16x16x32_bf16 v[78:81], v[156:159], v[224:227], v[78:81]
	v_mfma_f32_16x16x32_bf16 v[74:77], v[176:179], v[224:227], v[74:77]
	s_setprio 0
	s_setprio 1
	v_mfma_f32_16x16x32_bf16 v[118:121], v[180:183], v[196:199], v[118:121]
	v_mfma_f32_16x16x32_bf16 v[114:117], v[188:191], v[196:199], v[114:117]
	v_mfma_f32_16x16x32_bf16 v[102:105], v[180:183], v[204:207], v[102:105]
	v_mfma_f32_16x16x32_bf16 v[98:101], v[188:191], v[204:207], v[98:101]
	v_mfma_f32_16x16x32_bf16 v[86:89], v[180:183], v[212:215], v[86:89]
	v_mfma_f32_16x16x32_bf16 v[82:85], v[188:191], v[212:215], v[82:85]
	v_mfma_f32_16x16x32_bf16 v[70:73], v[180:183], v[220:223], v[70:73]
	v_mfma_f32_16x16x32_bf16 v[66:69], v[188:191], v[220:223], v[66:69]
	v_mfma_f32_16x16x32_bf16 v[118:121], v[184:187], v[200:203], v[118:121]
	v_mfma_f32_16x16x32_bf16 v[114:117], v[192:195], v[200:203], v[114:117]
	v_mfma_f32_16x16x32_bf16 v[102:105], v[184:187], v[208:211], v[102:105]
	v_mfma_f32_16x16x32_bf16 v[98:101], v[192:195], v[208:211], v[98:101]
	v_mfma_f32_16x16x32_bf16 v[86:89], v[184:187], v[216:219], v[86:89]
	v_mfma_f32_16x16x32_bf16 v[82:85], v[192:195], v[216:219], v[82:85]
	v_mfma_f32_16x16x32_bf16 v[70:73], v[184:187], v[224:227], v[70:73]
	v_mfma_f32_16x16x32_bf16 v[66:69], v[192:195], v[224:227], v[66:69]
	s_setprio 0
	s_barrier
	s_add_i32 s64, s72, s78
	v_lshl_add_u64 v[228:229], v[228:229], 0, s[20:21]
	s_mov_b32 m0, s64
	ds_read_b128 v[196:199], v168 offset:49152
	ds_read_b128 v[200:203], v168 offset:50176
	ds_read_b128 v[204:207], v168 offset:51200
	ds_read_b128 v[208:211], v168 offset:52224
	ds_read_b128 v[212:215], v168 offset:53248
	ds_read_b128 v[216:219], v168 offset:54272
	ds_read_b128 v[220:223], v168 offset:55296
	ds_read_b128 v[224:227], v168 offset:56320
	global_load_lds_dwordx4 v[228:229], off
	s_add_i32 m0, s64, 0x2000
	s_add_u32 s62, s62, 0x80080
	v_lshl_add_u64 v[228:229], v[230:231], 0, s[20:21]
	s_addc_u32 s63, s63, 0
	s_add_i32 s64, s73, s78
	global_load_lds_dwordx4 v[228:229], off
	v_lshl_add_u64 v[228:229], s[62:63], 0, v[134:135]
	s_mov_b32 m0, s64
	s_nop 0
	global_load_lds_dwordx4 v[228:229], off
	v_lshl_add_u64 v[228:229], s[62:63], 0, v[138:139]
	s_add_i32 m0, s64, 0x2000
	s_nop 0
	global_load_lds_dwordx4 v[228:229], off
	v_lshl_add_u64 v[228:229], v[232:233], 0, s[20:21]
	s_mov_b32 m0, s90
	s_nop 0
	global_load_lds_dwordx4 v[228:229], off
	v_lshl_add_u64 v[228:229], v[234:235], 0, s[20:21]
	s_mov_b32 m0, s91
	s_nop 0
	global_load_lds_dwordx4 v[228:229], off
	s_waitcnt vmcnt(8)
	s_waitcnt lgkmcnt(0)
	s_barrier
	s_setprio 1
	s_waitcnt lgkmcnt(0)
	v_mfma_f32_16x16x32_bf16 v[62:65], v[152:155], v[196:199], v[62:65]
	v_mfma_f32_16x16x32_bf16 v[58:61], v[172:175], v[196:199], v[58:61]
	v_mfma_f32_16x16x32_bf16 v[46:49], v[152:155], v[204:207], v[46:49]
	v_mfma_f32_16x16x32_bf16 v[42:45], v[172:175], v[204:207], v[42:45]
	v_mfma_f32_16x16x32_bf16 v[30:33], v[152:155], v[212:215], v[30:33]
	v_mfma_f32_16x16x32_bf16 v[26:29], v[172:175], v[212:215], v[26:29]
	v_mfma_f32_16x16x32_bf16 v[14:17], v[152:155], v[220:223], v[14:17]
	v_mfma_f32_16x16x32_bf16 v[10:13], v[172:175], v[220:223], v[10:13]
	v_mfma_f32_16x16x32_bf16 v[62:65], v[156:159], v[200:203], v[62:65]
	v_mfma_f32_16x16x32_bf16 v[58:61], v[176:179], v[200:203], v[58:61]
	v_mfma_f32_16x16x32_bf16 v[46:49], v[156:159], v[208:211], v[46:49]
	v_mfma_f32_16x16x32_bf16 v[42:45], v[176:179], v[208:211], v[42:45]
	v_mfma_f32_16x16x32_bf16 v[30:33], v[156:159], v[216:219], v[30:33]
	v_mfma_f32_16x16x32_bf16 v[26:29], v[176:179], v[216:219], v[26:29]
	v_mfma_f32_16x16x32_bf16 v[14:17], v[156:159], v[224:227], v[14:17]
	v_mfma_f32_16x16x32_bf16 v[10:13], v[176:179], v[224:227], v[10:13]
	s_setprio 0
	s_setprio 1
	v_mfma_f32_16x16x32_bf16 v[54:57], v[180:183], v[196:199], v[54:57]
	v_mfma_f32_16x16x32_bf16 v[50:53], v[188:191], v[196:199], v[50:53]
	v_mfma_f32_16x16x32_bf16 v[38:41], v[180:183], v[204:207], v[38:41]
	v_mfma_f32_16x16x32_bf16 v[34:37], v[188:191], v[204:207], v[34:37]
	v_mfma_f32_16x16x32_bf16 v[22:25], v[180:183], v[212:215], v[22:25]
	v_mfma_f32_16x16x32_bf16 v[18:21], v[188:191], v[212:215], v[18:21]
	v_mfma_f32_16x16x32_bf16 v[6:9], v[180:183], v[220:223], v[6:9]
	v_mfma_f32_16x16x32_bf16 v[2:5], v[188:191], v[220:223], v[2:5]
	v_mfma_f32_16x16x32_bf16 v[54:57], v[184:187], v[200:203], v[54:57]
	v_mfma_f32_16x16x32_bf16 v[50:53], v[192:195], v[200:203], v[50:53]
	v_mfma_f32_16x16x32_bf16 v[38:41], v[184:187], v[208:211], v[38:41]
	v_mfma_f32_16x16x32_bf16 v[34:37], v[192:195], v[208:211], v[34:37]
	v_mfma_f32_16x16x32_bf16 v[22:25], v[184:187], v[216:219], v[22:25]
	v_mfma_f32_16x16x32_bf16 v[18:21], v[192:195], v[216:219], v[18:21]
	v_mfma_f32_16x16x32_bf16 v[6:9], v[184:187], v[224:227], v[6:9]
	v_mfma_f32_16x16x32_bf16 v[2:5], v[192:195], v[224:227], v[2:5]
	s_setprio 0
	s_add_i32 s74, s74, 2
	s_add_u32 s8, s8, 0x100
	s_addc_u32 s9, s9, 0
	s_add_u32 s49, s49, 0x100
	s_addc_u32 s61, s61, 0
	s_cmp_gt_u32 s74, 29
	s_barrier
	s_cbranch_scc0 .LBB0_266
	s_and_b64 vcc, exec, s[22:23]
	s_cbranch_vccz .LBB0_269
	s_barrier

.LBB0_447:
	ds_read_b128 v[150:153], v167
	ds_read_b128 v[154:157], v167 offset:1024
	ds_read_b128 v[174:177], v167 offset:2048
	ds_read_b128 v[178:181], v167 offset:3072
	ds_read_b128 v[182:185], v168
	ds_read_b128 v[186:189], v168 offset:1024
	ds_read_b128 v[190:193], v168 offset:2048
	ds_read_b128 v[194:197], v168 offset:3072
	s_add_u32 s44, s6, 0xffe00080
	s_addc_u32 s45, s7, -1
	s_cmp_eq_u32 s74, 4
	s_cselect_b32 s49, s1, s45
	s_cselect_b32 s48, s5, s44
	s_cselect_b32 s45, s12, s39
	s_cselect_b32 s44, s13, s25
	v_lshl_add_u64 v[158:159], s[6:7], 0, v[140:141]
	s_add_i32 m0, s62, 0xc000
	ds_read_b128 v[198:201], v169
	ds_read_b128 v[202:205], v169 offset:1024
	ds_read_b128 v[206:209], v169 offset:2048
	ds_read_b128 v[210:213], v169 offset:3072
	ds_read_b128 v[214:217], v169 offset:4096
	ds_read_b128 v[218:221], v169 offset:5120
	ds_read_b128 v[222:225], v169 offset:6144
	ds_read_b128 v[226:229], v169 offset:7168
	global_load_lds_dwordx4 v[158:159], off
	v_lshl_add_u64 v[158:159], s[6:7], 0, v[142:143]
	s_add_i32 m0, s62, 0xe000
	s_nop 0
	global_load_lds_dwordx4 v[158:159], off
	s_waitcnt vmcnt(8)
	s_waitcnt lgkmcnt(0)
	s_barrier
	s_setprio 1
	s_waitcnt lgkmcnt(0)
	v_mfma_f32_16x16x32_bf16 v[126:129], v[150:153], v[198:201], v[126:129]
	v_mfma_f32_16x16x32_bf16 v[122:125], v[174:177], v[198:201], v[122:125]
	v_mfma_f32_16x16x32_bf16 v[110:113], v[150:153], v[206:209], v[110:113]
	v_mfma_f32_16x16x32_bf16 v[106:109], v[174:177], v[206:209], v[106:109]
	v_mfma_f32_16x16x32_bf16 v[94:97], v[150:153], v[214:217], v[94:97]
	v_mfma_f32_16x16x32_bf16 v[90:93], v[174:177], v[214:217], v[90:93]
	v_mfma_f32_16x16x32_bf16 v[78:81], v[150:153], v[222:225], v[78:81]
	v_mfma_f32_16x16x32_bf16 v[74:77], v[174:177], v[222:225], v[74:77]
	v_mfma_f32_16x16x32_bf16 v[126:129], v[154:157], v[202:205], v[126:129]
	v_mfma_f32_16x16x32_bf16 v[122:125], v[178:181], v[202:205], v[122:125]
	v_mfma_f32_16x16x32_bf16 v[110:113], v[154:157], v[210:213], v[110:113]
	v_mfma_f32_16x16x32_bf16 v[106:109], v[178:181], v[210:213], v[106:109]
	v_mfma_f32_16x16x32_bf16 v[94:97], v[154:157], v[218:221], v[94:97]
	v_mfma_f32_16x16x32_bf16 v[90:93], v[178:181], v[218:221], v[90:93]
	v_mfma_f32_16x16x32_bf16 v[78:81], v[154:157], v[226:229], v[78:81]
	v_mfma_f32_16x16x32_bf16 v[74:77], v[178:181], v[226:229], v[74:77]
	s_setprio 0
	s_setprio 1
	v_mfma_f32_16x16x32_bf16 v[118:121], v[182:185], v[198:201], v[118:121]
	v_mfma_f32_16x16x32_bf16 v[114:117], v[190:193], v[198:201], v[114:117]
	v_mfma_f32_16x16x32_bf16 v[102:105], v[182:185], v[206:209], v[102:105]
	v_mfma_f32_16x16x32_bf16 v[98:101], v[190:193], v[206:209], v[98:101]
	v_mfma_f32_16x16x32_bf16 v[86:89], v[182:185], v[214:217], v[86:89]
	v_mfma_f32_16x16x32_bf16 v[82:85], v[190:193], v[214:217], v[82:85]
	v_mfma_f32_16x16x32_bf16 v[70:73], v[182:185], v[222:225], v[70:73]
	v_mfma_f32_16x16x32_bf16 v[66:69], v[190:193], v[222:225], v[66:69]
	v_mfma_f32_16x16x32_bf16 v[118:121], v[186:189], v[202:205], v[118:121]
	v_mfma_f32_16x16x32_bf16 v[114:117], v[194:197], v[202:205], v[114:117]
	v_mfma_f32_16x16x32_bf16 v[102:105], v[186:189], v[210:213], v[102:105]
	v_mfma_f32_16x16x32_bf16 v[98:101], v[194:197], v[210:213], v[98:101]
	v_mfma_f32_16x16x32_bf16 v[86:89], v[186:189], v[218:221], v[86:89]
	v_mfma_f32_16x16x32_bf16 v[82:85], v[194:197], v[218:221], v[82:85]
	v_mfma_f32_16x16x32_bf16 v[70:73], v[186:189], v[226:229], v[70:73]
	v_mfma_f32_16x16x32_bf16 v[66:69], v[194:197], v[226:229], v[66:69]
	s_setprio 0
	s_barrier
	s_add_i32 s72, s79, s61
	v_lshl_add_u64 v[158:159], s[44:45], 0, v[132:133]
	s_mov_b32 m0, s72
	ds_read_b128 v[198:201], v169 offset:16384
	ds_read_b128 v[202:205], v169 offset:17408
	ds_read_b128 v[206:209], v169 offset:18432
	ds_read_b128 v[210:213], v169 offset:19456
	ds_read_b128 v[214:217], v169 offset:20480
	ds_read_b128 v[218:221], v169 offset:21504
	ds_read_b128 v[222:225], v169 offset:22528
	ds_read_b128 v[226:229], v169 offset:23552
	global_load_lds_dwordx4 v[158:159], off
	s_add_i32 m0, s72, 0x2000
	s_add_u32 s84, s44, 0x20000
	v_lshl_add_u64 v[230:231], s[44:45], 0, v[136:137]
	s_addc_u32 s85, s45, 0
	s_add_i32 s72, s80, s61
	global_load_lds_dwordx4 v[230:231], off
	v_lshl_add_u64 v[232:233], s[84:85], 0, v[132:133]
	s_mov_b32 m0, s72
	v_lshl_add_u64 v[234:235], s[48:49], 0, v[134:135]
	global_load_lds_dwordx4 v[232:233], off
	v_lshl_add_u64 v[232:233], s[84:85], 0, v[136:137]
	s_add_i32 m0, s72, 0x2000
	s_nop 0
	global_load_lds_dwordx4 v[232:233], off
	v_lshl_add_u64 v[232:233], s[48:49], 0, v[130:131]
	s_mov_b32 m0, s62
	s_nop 0
	global_load_lds_dwordx4 v[232:233], off
	s_mov_b32 m0, s63
	s_nop 0
	global_load_lds_dwordx4 v[234:235], off
	s_waitcnt vmcnt(8)
	s_waitcnt lgkmcnt(0)
	s_barrier
	s_setprio 1
	s_waitcnt lgkmcnt(0)
	v_mfma_f32_16x16x32_bf16 v[62:65], v[150:153], v[198:201], v[62:65]
	v_mfma_f32_16x16x32_bf16 v[58:61], v[174:177], v[198:201], v[58:61]
	v_mfma_f32_16x16x32_bf16 v[46:49], v[150:153], v[206:209], v[46:49]
	v_mfma_f32_16x16x32_bf16 v[42:45], v[174:177], v[206:209], v[42:45]
	v_mfma_f32_16x16x32_bf16 v[30:33], v[150:153], v[214:217], v[30:33]
	v_mfma_f32_16x16x32_bf16 v[26:29], v[174:177], v[214:217], v[26:29]
	v_mfma_f32_16x16x32_bf16 v[14:17], v[150:153], v[222:225], v[14:17]
	v_mfma_f32_16x16x32_bf16 v[10:13], v[174:177], v[222:225], v[10:13]
	v_mfma_f32_16x16x32_bf16 v[62:65], v[154:157], v[202:205], v[62:65]
	v_mfma_f32_16x16x32_bf16 v[58:61], v[178:181], v[202:205], v[58:61]
	v_mfma_f32_16x16x32_bf16 v[46:49], v[154:157], v[210:213], v[46:49]
	v_mfma_f32_16x16x32_bf16 v[42:45], v[178:181], v[210:213], v[42:45]
	v_mfma_f32_16x16x32_bf16 v[30:33], v[154:157], v[218:221], v[30:33]
	v_mfma_f32_16x16x32_bf16 v[26:29], v[178:181], v[218:221], v[26:29]
	v_mfma_f32_16x16x32_bf16 v[14:17], v[154:157], v[226:229], v[14:17]
	v_mfma_f32_16x16x32_bf16 v[10:13], v[178:181], v[226:229], v[10:13]
	s_setprio 0
	s_setprio 1
	v_mfma_f32_16x16x32_bf16 v[54:57], v[182:185], v[198:201], v[54:57]
	v_mfma_f32_16x16x32_bf16 v[50:53], v[190:193], v[198:201], v[50:53]
	v_mfma_f32_16x16x32_bf16 v[38:41], v[182:185], v[206:209], v[38:41]
	v_mfma_f32_16x16x32_bf16 v[34:37], v[190:193], v[206:209], v[34:37]
	v_mfma_f32_16x16x32_bf16 v[22:25], v[182:185], v[214:217], v[22:25]
	v_mfma_f32_16x16x32_bf16 v[18:21], v[190:193], v[214:217], v[18:21]
	v_mfma_f32_16x16x32_bf16 v[6:9], v[182:185], v[222:225], v[6:9]
	v_mfma_f32_16x16x32_bf16 v[2:5], v[190:193], v[222:225], v[2:5]
	v_mfma_f32_16x16x32_bf16 v[54:57], v[186:189], v[202:205], v[54:57]
	v_mfma_f32_16x16x32_bf16 v[50:53], v[194:197], v[202:205], v[50:53]
	v_mfma_f32_16x16x32_bf16 v[38:41], v[186:189], v[210:213], v[38:41]
	v_mfma_f32_16x16x32_bf16 v[34:37], v[194:197], v[210:213], v[34:37]
	v_mfma_f32_16x16x32_bf16 v[22:25], v[186:189], v[218:221], v[22:25]
	v_mfma_f32_16x16x32_bf16 v[18:21], v[194:197], v[218:221], v[18:21]
	v_mfma_f32_16x16x32_bf16 v[6:9], v[186:189], v[226:229], v[6:9]
	v_mfma_f32_16x16x32_bf16 v[2:5], v[194:197], v[226:229], v[2:5]
	s_setprio 0
	s_barrier
	s_add_i32 s72, 0, 0x18000
	v_add_u32_e32 v173, s72, v161
	s_add_i32 s73, 0, 0x1c000
	ds_read_b128 v[150:153], v173
	ds_read_b128 v[154:157], v173 offset:1024
	ds_read_b128 v[174:177], v173 offset:2048
	ds_read_b128 v[178:181], v173 offset:3072
	v_add_u32_e32 v173, s73, v161
	ds_read_b128 v[182:185], v173
	ds_read_b128 v[186:189], v173 offset:1024
	ds_read_b128 v[190:193], v173 offset:2048
	ds_read_b128 v[194:197], v173 offset:3072
	s_add_u32 s48, s48, 0x200000
	s_addc_u32 s49, s49, 0
	s_mov_b32 m0, s64
	v_lshl_add_u64 v[236:237], s[48:49], 0, v[130:131]
	ds_read_b128 v[198:201], v169 offset:32768
	ds_read_b128 v[202:205], v169 offset:33792
	ds_read_b128 v[206:209], v169 offset:34816
	ds_read_b128 v[210:213], v169 offset:35840
	ds_read_b128 v[214:217], v169 offset:36864
	ds_read_b128 v[218:221], v169 offset:37888
	ds_read_b128 v[222:225], v169 offset:38912
	ds_read_b128 v[226:229], v169 offset:39936
	global_load_lds_dwordx4 v[236:237], off
	v_lshl_add_u64 v[236:237], s[48:49], 0, v[134:135]
	s_mov_b32 m0, s65
	s_nop 0
	global_load_lds_dwordx4 v[236:237], off
	s_waitcnt vmcnt(8)
	s_waitcnt lgkmcnt(0)
	s_barrier
	s_setprio 1
	s_waitcnt lgkmcnt(0)
	v_mfma_f32_16x16x32_bf16 v[126:129], v[150:153], v[198:201], v[126:129]
	v_mfma_f32_16x16x32_bf16 v[122:125], v[174:177], v[198:201], v[122:125]
	v_mfma_f32_16x16x32_bf16 v[110:113], v[150:153], v[206:209], v[110:113]
	v_mfma_f32_16x16x32_bf16 v[106:109], v[174:177], v[206:209], v[106:109]
	v_mfma_f32_16x16x32_bf16 v[94:97], v[150:153], v[214:217], v[94:97]
	v_mfma_f32_16x16x32_bf16 v[90:93], v[174:177], v[214:217], v[90:93]
	v_mfma_f32_16x16x32_bf16 v[78:81], v[150:153], v[222:225], v[78:81]
	v_mfma_f32_16x16x32_bf16 v[74:77], v[174:177], v[222:225], v[74:77]
	v_mfma_f32_16x16x32_bf16 v[126:129], v[154:157], v[202:205], v[126:129]
	v_mfma_f32_16x16x32_bf16 v[122:125], v[178:181], v[202:205], v[122:125]
	v_mfma_f32_16x16x32_bf16 v[110:113], v[154:157], v[210:213], v[110:113]
	v_mfma_f32_16x16x32_bf16 v[106:109], v[178:181], v[210:213], v[106:109]
	v_mfma_f32_16x16x32_bf16 v[94:97], v[154:157], v[218:221], v[94:97]
	v_mfma_f32_16x16x32_bf16 v[90:93], v[178:181], v[218:221], v[90:93]
	v_mfma_f32_16x16x32_bf16 v[78:81], v[154:157], v[226:229], v[78:81]
	v_mfma_f32_16x16x32_bf16 v[74:77], v[178:181], v[226:229], v[74:77]
	s_setprio 0
	s_setprio 1
	v_mfma_f32_16x16x32_bf16 v[118:121], v[182:185], v[198:201], v[118:121]
	v_mfma_f32_16x16x32_bf16 v[114:117], v[190:193], v[198:201], v[114:117]
	v_mfma_f32_16x16x32_bf16 v[102:105], v[182:185], v[206:209], v[102:105]
	v_mfma_f32_16x16x32_bf16 v[98:101], v[190:193], v[206:209], v[98:101]
	v_mfma_f32_16x16x32_bf16 v[86:89], v[182:185], v[214:217], v[86:89]
	v_mfma_f32_16x16x32_bf16 v[82:85], v[190:193], v[214:217], v[82:85]
	v_mfma_f32_16x16x32_bf16 v[70:73], v[182:185], v[222:225], v[70:73]
	v_mfma_f32_16x16x32_bf16 v[66:69], v[190:193], v[222:225], v[66:69]
	v_mfma_f32_16x16x32_bf16 v[118:121], v[186:189], v[202:205], v[118:121]
	v_mfma_f32_16x16x32_bf16 v[114:117], v[194:197], v[202:205], v[114:117]
	v_mfma_f32_16x16x32_bf16 v[102:105], v[186:189], v[210:213], v[102:105]
	v_mfma_f32_16x16x32_bf16 v[98:101], v[194:197], v[210:213], v[98:101]
	v_mfma_f32_16x16x32_bf16 v[86:89], v[186:189], v[218:221], v[86:89]
	v_mfma_f32_16x16x32_bf16 v[82:85], v[194:197], v[218:221], v[82:85]
	v_mfma_f32_16x16x32_bf16 v[70:73], v[186:189], v[226:229], v[70:73]
	v_mfma_f32_16x16x32_bf16 v[66:69], v[194:197], v[226:229], v[66:69]
	s_setprio 0
	s_barrier
	s_add_i32 s48, s72, s61
	v_lshl_add_u64 v[158:159], v[158:159], 0, s[20:21]
	s_mov_b32 m0, s48
	ds_read_b128 v[198:201], v169 offset:49152
	ds_read_b128 v[202:205], v169 offset:50176
	ds_read_b128 v[206:209], v169 offset:51200
	ds_read_b128 v[210:213], v169 offset:52224
	ds_read_b128 v[214:217], v169 offset:53248
	ds_read_b128 v[218:221], v169 offset:54272
	ds_read_b128 v[222:225], v169 offset:55296
	ds_read_b128 v[226:229], v169 offset:56320
	global_load_lds_dwordx4 v[158:159], off
	s_add_i32 m0, s48, 0x2000
	s_add_u32 s44, s44, 0x20080
	v_lshl_add_u64 v[158:159], v[230:231], 0, s[20:21]
	s_addc_u32 s45, s45, 0
	s_add_i32 s48, s73, s61
	global_load_lds_dwordx4 v[158:159], off
	v_lshl_add_u64 v[158:159], s[44:45], 0, v[132:133]
	s_mov_b32 m0, s48
	s_nop 0
	global_load_lds_dwordx4 v[158:159], off
	v_lshl_add_u64 v[158:159], s[44:45], 0, v[136:137]
	s_add_i32 m0, s48, 0x2000
	s_nop 0
	global_load_lds_dwordx4 v[158:159], off
	v_lshl_add_u64 v[158:159], v[232:233], 0, s[20:21]
	s_mov_b32 m0, s77
	s_nop 0
	global_load_lds_dwordx4 v[158:159], off
	v_lshl_add_u64 v[158:159], v[234:235], 0, s[20:21]
	s_mov_b32 m0, s78
	s_nop 0
	global_load_lds_dwordx4 v[158:159], off
	s_waitcnt vmcnt(8)
	s_waitcnt lgkmcnt(0)
	s_barrier
	s_setprio 1
	s_waitcnt lgkmcnt(0)
	v_mfma_f32_16x16x32_bf16 v[62:65], v[150:153], v[198:201], v[62:65]
	v_mfma_f32_16x16x32_bf16 v[58:61], v[174:177], v[198:201], v[58:61]
	v_mfma_f32_16x16x32_bf16 v[46:49], v[150:153], v[206:209], v[46:49]
	v_mfma_f32_16x16x32_bf16 v[42:45], v[174:177], v[206:209], v[42:45]
	v_mfma_f32_16x16x32_bf16 v[30:33], v[150:153], v[214:217], v[30:33]
	v_mfma_f32_16x16x32_bf16 v[26:29], v[174:177], v[214:217], v[26:29]
	v_mfma_f32_16x16x32_bf16 v[14:17], v[150:153], v[222:225], v[14:17]
	v_mfma_f32_16x16x32_bf16 v[10:13], v[174:177], v[222:225], v[10:13]
	v_mfma_f32_16x16x32_bf16 v[62:65], v[154:157], v[202:205], v[62:65]
	v_mfma_f32_16x16x32_bf16 v[58:61], v[178:181], v[202:205], v[58:61]
	v_mfma_f32_16x16x32_bf16 v[46:49], v[154:157], v[210:213], v[46:49]
	v_mfma_f32_16x16x32_bf16 v[42:45], v[178:181], v[210:213], v[42:45]
	v_mfma_f32_16x16x32_bf16 v[30:33], v[154:157], v[218:221], v[30:33]
	v_mfma_f32_16x16x32_bf16 v[26:29], v[178:181], v[218:221], v[26:29]
	v_mfma_f32_16x16x32_bf16 v[14:17], v[154:157], v[226:229], v[14:17]
	v_mfma_f32_16x16x32_bf16 v[10:13], v[178:181], v[226:229], v[10:13]
	s_setprio 0
	s_setprio 1
	v_mfma_f32_16x16x32_bf16 v[54:57], v[182:185], v[198:201], v[54:57]
	v_mfma_f32_16x16x32_bf16 v[50:53], v[190:193], v[198:201], v[50:53]
	v_mfma_f32_16x16x32_bf16 v[38:41], v[182:185], v[206:209], v[38:41]
	v_mfma_f32_16x16x32_bf16 v[34:37], v[190:193], v[206:209], v[34:37]
	v_mfma_f32_16x16x32_bf16 v[22:25], v[182:185], v[214:217], v[22:25]
	v_mfma_f32_16x16x32_bf16 v[18:21], v[190:193], v[214:217], v[18:21]
	v_mfma_f32_16x16x32_bf16 v[6:9], v[182:185], v[222:225], v[6:9]
	v_mfma_f32_16x16x32_bf16 v[2:5], v[190:193], v[222:225], v[2:5]
	v_mfma_f32_16x16x32_bf16 v[54:57], v[186:189], v[202:205], v[54:57]
	v_mfma_f32_16x16x32_bf16 v[50:53], v[194:197], v[202:205], v[50:53]
	v_mfma_f32_16x16x32_bf16 v[38:41], v[186:189], v[210:213], v[38:41]
	v_mfma_f32_16x16x32_bf16 v[34:37], v[194:197], v[210:213], v[34:37]
	v_mfma_f32_16x16x32_bf16 v[22:25], v[186:189], v[218:221], v[22:25]
	v_mfma_f32_16x16x32_bf16 v[18:21], v[194:197], v[218:221], v[18:21]
	v_mfma_f32_16x16x32_bf16 v[6:9], v[186:189], v[226:229], v[6:9]
	v_mfma_f32_16x16x32_bf16 v[2:5], v[194:197], v[226:229], v[2:5]
	s_setprio 0
	s_add_i32 s74, s74, 2
	s_add_u32 s6, s6, 0x100
	s_addc_u32 s7, s7, 0
	s_add_u32 s25, s25, 0x100
	s_addc_u32 s39, s39, 0
	s_cmp_gt_u32 s74, 5
	s_barrier
	s_cbranch_scc0 .LBB0_447
	s_and_b64 vcc, exec, s[22:23]
	s_cbranch_vccz .LBB0_450
	s_barrier

.LBB0_783:
	ds_read_b128 v[130:133], v164
	ds_read_b128 v[134:137], v164 offset:1024
	ds_read_b128 v[156:159], v164 offset:2048
	ds_read_b128 v[168:171], v164 offset:3072
	ds_read_b128 v[172:175], v165
	ds_read_b128 v[178:181], v165 offset:1024
	ds_read_b128 v[182:185], v165 offset:2048
	ds_read_b128 v[186:189], v165 offset:3072
	s_add_u32 s48, s44, 0xfffc0080
	s_addc_u32 s49, s45, -1
	s_cmp_eq_u32 s79, 12
	s_cselect_b32 s53, s13, s49
	s_cselect_b32 s52, s25, s48
	s_cselect_b32 s49, s23, s78
	s_cselect_b32 s48, s74, s75
	v_lshl_add_u64 v[160:161], s[44:45], 0, v[148:149]
	s_add_i32 m0, s43, 0xc000
	ds_read_b128 v[190:193], v166
	ds_read_b128 v[194:197], v166 offset:1024
	ds_read_b128 v[198:201], v166 offset:2048
	ds_read_b128 v[202:205], v166 offset:3072
	ds_read_b128 v[206:209], v166 offset:4096
	ds_read_b128 v[210:213], v166 offset:5120
	ds_read_b128 v[214:217], v166 offset:6144
	ds_read_b128 v[218:221], v166 offset:7168
	global_load_lds_dwordx4 v[160:161], off
	v_lshl_add_u64 v[160:161], s[44:45], 0, v[150:151]
	s_add_i32 m0, s43, 0xe000
	s_nop 0
	global_load_lds_dwordx4 v[160:161], off
	s_waitcnt vmcnt(8)
	s_waitcnt lgkmcnt(0)
	s_barrier
	s_setprio 1
	s_waitcnt lgkmcnt(0)
	v_mfma_f32_16x16x32_bf16 v[126:129], v[130:133], v[190:193], v[126:129]
	v_mfma_f32_16x16x32_bf16 v[122:125], v[156:159], v[190:193], v[122:125]
	v_mfma_f32_16x16x32_bf16 v[110:113], v[130:133], v[198:201], v[110:113]
	v_mfma_f32_16x16x32_bf16 v[106:109], v[156:159], v[198:201], v[106:109]
	v_mfma_f32_16x16x32_bf16 v[94:97], v[130:133], v[206:209], v[94:97]
	v_mfma_f32_16x16x32_bf16 v[90:93], v[156:159], v[206:209], v[90:93]
	v_mfma_f32_16x16x32_bf16 v[78:81], v[130:133], v[214:217], v[78:81]
	v_mfma_f32_16x16x32_bf16 v[74:77], v[156:159], v[214:217], v[74:77]
	v_mfma_f32_16x16x32_bf16 v[126:129], v[134:137], v[194:197], v[126:129]
	v_mfma_f32_16x16x32_bf16 v[122:125], v[168:171], v[194:197], v[122:125]
	v_mfma_f32_16x16x32_bf16 v[110:113], v[134:137], v[202:205], v[110:113]
	v_mfma_f32_16x16x32_bf16 v[106:109], v[168:171], v[202:205], v[106:109]
	v_mfma_f32_16x16x32_bf16 v[94:97], v[134:137], v[210:213], v[94:97]
	v_mfma_f32_16x16x32_bf16 v[90:93], v[168:171], v[210:213], v[90:93]
	v_mfma_f32_16x16x32_bf16 v[78:81], v[134:137], v[218:221], v[78:81]
	v_mfma_f32_16x16x32_bf16 v[74:77], v[168:171], v[218:221], v[74:77]
	s_setprio 0
	s_setprio 1
	v_mfma_f32_16x16x32_bf16 v[118:121], v[172:175], v[190:193], v[118:121]
	v_mfma_f32_16x16x32_bf16 v[114:117], v[182:185], v[190:193], v[114:117]
	v_mfma_f32_16x16x32_bf16 v[102:105], v[172:175], v[198:201], v[102:105]
	v_mfma_f32_16x16x32_bf16 v[98:101], v[182:185], v[198:201], v[98:101]
	v_mfma_f32_16x16x32_bf16 v[86:89], v[172:175], v[206:209], v[86:89]
	v_mfma_f32_16x16x32_bf16 v[82:85], v[182:185], v[206:209], v[82:85]
	v_mfma_f32_16x16x32_bf16 v[70:73], v[172:175], v[214:217], v[70:73]
	v_mfma_f32_16x16x32_bf16 v[66:69], v[182:185], v[214:217], v[66:69]
	v_mfma_f32_16x16x32_bf16 v[118:121], v[178:181], v[194:197], v[118:121]
	v_mfma_f32_16x16x32_bf16 v[114:117], v[186:189], v[194:197], v[114:117]
	v_mfma_f32_16x16x32_bf16 v[102:105], v[178:181], v[202:205], v[102:105]
	v_mfma_f32_16x16x32_bf16 v[98:101], v[186:189], v[202:205], v[98:101]
	v_mfma_f32_16x16x32_bf16 v[86:89], v[178:181], v[210:213], v[86:89]
	v_mfma_f32_16x16x32_bf16 v[82:85], v[186:189], v[210:213], v[82:85]
	v_mfma_f32_16x16x32_bf16 v[70:73], v[178:181], v[218:221], v[70:73]
	v_mfma_f32_16x16x32_bf16 v[66:69], v[186:189], v[218:221], v[66:69]
	s_setprio 0
	s_barrier
	s_add_i32 s72, s76, s62
	v_lshl_add_u64 v[160:161], s[48:49], 0, v[142:143]
	s_mov_b32 m0, s72
	ds_read_b128 v[190:193], v166 offset:16384
	ds_read_b128 v[194:197], v166 offset:17408
	ds_read_b128 v[198:201], v166 offset:18432
	ds_read_b128 v[202:205], v166 offset:19456
	ds_read_b128 v[206:209], v166 offset:20480
	ds_read_b128 v[210:213], v166 offset:21504
	ds_read_b128 v[214:217], v166 offset:22528
	ds_read_b128 v[218:221], v166 offset:23552
	global_load_lds_dwordx4 v[160:161], off
	s_add_i32 m0, s72, 0x2000
	s_add_u32 s72, s48, 0x40000
	v_lshl_add_u64 v[222:223], s[48:49], 0, v[138:139]
	s_addc_u32 s73, s49, 0
	s_add_i32 s80, s77, s62
	global_load_lds_dwordx4 v[222:223], off
	v_lshl_add_u64 v[224:225], s[72:73], 0, v[142:143]
	s_mov_b32 m0, s80
	v_lshl_add_u64 v[226:227], s[52:53], 0, v[140:141]
	global_load_lds_dwordx4 v[224:225], off
	v_lshl_add_u64 v[224:225], s[72:73], 0, v[138:139]
	s_add_i32 m0, s80, 0x2000
	s_nop 0
	global_load_lds_dwordx4 v[224:225], off
	v_lshl_add_u64 v[224:225], s[52:53], 0, v[144:145]
	s_mov_b32 m0, s43
	s_nop 0
	global_load_lds_dwordx4 v[224:225], off
	s_mov_b32 m0, s63
	s_nop 0
	global_load_lds_dwordx4 v[226:227], off
	s_waitcnt vmcnt(8)
	s_waitcnt lgkmcnt(0)
	s_barrier
	s_setprio 1
	s_waitcnt lgkmcnt(0)
	v_mfma_f32_16x16x32_bf16 v[62:65], v[130:133], v[190:193], v[62:65]
	v_mfma_f32_16x16x32_bf16 v[58:61], v[156:159], v[190:193], v[58:61]
	v_mfma_f32_16x16x32_bf16 v[46:49], v[130:133], v[198:201], v[46:49]
	v_mfma_f32_16x16x32_bf16 v[42:45], v[156:159], v[198:201], v[42:45]
	v_mfma_f32_16x16x32_bf16 v[30:33], v[130:133], v[206:209], v[30:33]
	v_mfma_f32_16x16x32_bf16 v[26:29], v[156:159], v[206:209], v[26:29]
	v_mfma_f32_16x16x32_bf16 v[14:17], v[130:133], v[214:217], v[14:17]
	v_mfma_f32_16x16x32_bf16 v[10:13], v[156:159], v[214:217], v[10:13]
	v_mfma_f32_16x16x32_bf16 v[62:65], v[134:137], v[194:197], v[62:65]
	v_mfma_f32_16x16x32_bf16 v[58:61], v[168:171], v[194:197], v[58:61]
	v_mfma_f32_16x16x32_bf16 v[46:49], v[134:137], v[202:205], v[46:49]
	v_mfma_f32_16x16x32_bf16 v[42:45], v[168:171], v[202:205], v[42:45]
	v_mfma_f32_16x16x32_bf16 v[30:33], v[134:137], v[210:213], v[30:33]
	v_mfma_f32_16x16x32_bf16 v[26:29], v[168:171], v[210:213], v[26:29]
	v_mfma_f32_16x16x32_bf16 v[14:17], v[134:137], v[218:221], v[14:17]
	v_mfma_f32_16x16x32_bf16 v[10:13], v[168:171], v[218:221], v[10:13]
	s_setprio 0
	s_setprio 1
	v_mfma_f32_16x16x32_bf16 v[54:57], v[172:175], v[190:193], v[54:57]
	v_mfma_f32_16x16x32_bf16 v[50:53], v[182:185], v[190:193], v[50:53]
	v_mfma_f32_16x16x32_bf16 v[38:41], v[172:175], v[198:201], v[38:41]
	v_mfma_f32_16x16x32_bf16 v[34:37], v[182:185], v[198:201], v[34:37]
	v_mfma_f32_16x16x32_bf16 v[22:25], v[172:175], v[206:209], v[22:25]
	v_mfma_f32_16x16x32_bf16 v[18:21], v[182:185], v[206:209], v[18:21]
	v_mfma_f32_16x16x32_bf16 v[6:9], v[172:175], v[214:217], v[6:9]
	v_mfma_f32_16x16x32_bf16 v[2:5], v[182:185], v[214:217], v[2:5]
	v_mfma_f32_16x16x32_bf16 v[54:57], v[178:181], v[194:197], v[54:57]
	v_mfma_f32_16x16x32_bf16 v[50:53], v[186:189], v[194:197], v[50:53]
	v_mfma_f32_16x16x32_bf16 v[38:41], v[178:181], v[202:205], v[38:41]
	v_mfma_f32_16x16x32_bf16 v[34:37], v[186:189], v[202:205], v[34:37]
	v_mfma_f32_16x16x32_bf16 v[22:25], v[178:181], v[210:213], v[22:25]
	v_mfma_f32_16x16x32_bf16 v[18:21], v[186:189], v[210:213], v[18:21]
	v_mfma_f32_16x16x32_bf16 v[6:9], v[178:181], v[218:221], v[6:9]
	v_mfma_f32_16x16x32_bf16 v[2:5], v[186:189], v[218:221], v[2:5]
	s_setprio 0
	s_barrier
	s_add_i32 s72, 0, 0x18000
	v_add_u32_e32 v167, s72, v162
	s_add_i32 s73, 0, 0x1c000
	ds_read_b128 v[130:133], v167
	ds_read_b128 v[134:137], v167 offset:1024
	ds_read_b128 v[156:159], v167 offset:2048
	ds_read_b128 v[168:171], v167 offset:3072
	v_add_u32_e32 v167, s73, v162
	ds_read_b128 v[172:175], v167
	ds_read_b128 v[178:181], v167 offset:1024
	ds_read_b128 v[182:185], v167 offset:2048
	ds_read_b128 v[186:189], v167 offset:3072
	s_add_u32 s52, s52, 0x40000
	s_addc_u32 s53, s53, 0
	s_mov_b32 m0, s64
	v_lshl_add_u64 v[228:229], s[52:53], 0, v[144:145]
	ds_read_b128 v[190:193], v166 offset:32768
	ds_read_b128 v[194:197], v166 offset:33792
	ds_read_b128 v[198:201], v166 offset:34816
	ds_read_b128 v[202:205], v166 offset:35840
	ds_read_b128 v[206:209], v166 offset:36864
	ds_read_b128 v[210:213], v166 offset:37888
	ds_read_b128 v[214:217], v166 offset:38912
	ds_read_b128 v[218:221], v166 offset:39936
	global_load_lds_dwordx4 v[228:229], off
	v_lshl_add_u64 v[228:229], s[52:53], 0, v[140:141]
	s_mov_b32 m0, s65
	s_nop 0
	global_load_lds_dwordx4 v[228:229], off
	s_waitcnt vmcnt(8)
	s_waitcnt lgkmcnt(0)
	s_barrier
	s_setprio 1
	s_waitcnt lgkmcnt(0)
	v_mfma_f32_16x16x32_bf16 v[126:129], v[130:133], v[190:193], v[126:129]
	v_mfma_f32_16x16x32_bf16 v[122:125], v[156:159], v[190:193], v[122:125]
	v_mfma_f32_16x16x32_bf16 v[110:113], v[130:133], v[198:201], v[110:113]
	v_mfma_f32_16x16x32_bf16 v[106:109], v[156:159], v[198:201], v[106:109]
	v_mfma_f32_16x16x32_bf16 v[94:97], v[130:133], v[206:209], v[94:97]
	v_mfma_f32_16x16x32_bf16 v[90:93], v[156:159], v[206:209], v[90:93]
	v_mfma_f32_16x16x32_bf16 v[78:81], v[130:133], v[214:217], v[78:81]
	v_mfma_f32_16x16x32_bf16 v[74:77], v[156:159], v[214:217], v[74:77]
	v_mfma_f32_16x16x32_bf16 v[126:129], v[134:137], v[194:197], v[126:129]
	v_mfma_f32_16x16x32_bf16 v[122:125], v[168:171], v[194:197], v[122:125]
	v_mfma_f32_16x16x32_bf16 v[110:113], v[134:137], v[202:205], v[110:113]
	v_mfma_f32_16x16x32_bf16 v[106:109], v[168:171], v[202:205], v[106:109]
	v_mfma_f32_16x16x32_bf16 v[94:97], v[134:137], v[210:213], v[94:97]
	v_mfma_f32_16x16x32_bf16 v[90:93], v[168:171], v[210:213], v[90:93]
	v_mfma_f32_16x16x32_bf16 v[78:81], v[134:137], v[218:221], v[78:81]
	v_mfma_f32_16x16x32_bf16 v[74:77], v[168:171], v[218:221], v[74:77]
	s_setprio 0
	s_setprio 1
	v_mfma_f32_16x16x32_bf16 v[118:121], v[172:175], v[190:193], v[118:121]
	v_mfma_f32_16x16x32_bf16 v[114:117], v[182:185], v[190:193], v[114:117]
	v_mfma_f32_16x16x32_bf16 v[102:105], v[172:175], v[198:201], v[102:105]
	v_mfma_f32_16x16x32_bf16 v[98:101], v[182:185], v[198:201], v[98:101]
	v_mfma_f32_16x16x32_bf16 v[86:89], v[172:175], v[206:209], v[86:89]
	v_mfma_f32_16x16x32_bf16 v[82:85], v[182:185], v[206:209], v[82:85]
	v_mfma_f32_16x16x32_bf16 v[70:73], v[172:175], v[214:217], v[70:73]
	v_mfma_f32_16x16x32_bf16 v[66:69], v[182:185], v[214:217], v[66:69]
	v_mfma_f32_16x16x32_bf16 v[118:121], v[178:181], v[194:197], v[118:121]
	v_mfma_f32_16x16x32_bf16 v[114:117], v[186:189], v[194:197], v[114:117]
	v_mfma_f32_16x16x32_bf16 v[102:105], v[178:181], v[202:205], v[102:105]
	v_mfma_f32_16x16x32_bf16 v[98:101], v[186:189], v[202:205], v[98:101]
	v_mfma_f32_16x16x32_bf16 v[86:89], v[178:181], v[210:213], v[86:89]
	v_mfma_f32_16x16x32_bf16 v[82:85], v[186:189], v[210:213], v[82:85]
	v_mfma_f32_16x16x32_bf16 v[70:73], v[178:181], v[218:221], v[70:73]
	v_mfma_f32_16x16x32_bf16 v[66:69], v[186:189], v[218:221], v[66:69]
	s_setprio 0
	s_barrier
	s_add_i32 s52, s72, s62
	v_lshl_add_u64 v[160:161], v[160:161], 0, s[18:19]
	s_mov_b32 m0, s52
	ds_read_b128 v[190:193], v166 offset:49152
	ds_read_b128 v[194:197], v166 offset:50176
	ds_read_b128 v[198:201], v166 offset:51200
	ds_read_b128 v[202:205], v166 offset:52224
	ds_read_b128 v[206:209], v166 offset:53248
	ds_read_b128 v[210:213], v166 offset:54272
	ds_read_b128 v[214:217], v166 offset:55296
	ds_read_b128 v[218:221], v166 offset:56320
	global_load_lds_dwordx4 v[160:161], off
	s_add_i32 m0, s52, 0x2000
	s_add_u32 s48, s48, 0x40080
	v_lshl_add_u64 v[160:161], v[222:223], 0, s[18:19]
	s_addc_u32 s49, s49, 0
	s_add_i32 s52, s73, s62
	global_load_lds_dwordx4 v[160:161], off
	v_lshl_add_u64 v[160:161], s[48:49], 0, v[142:143]
	s_mov_b32 m0, s52
	s_nop 0
	global_load_lds_dwordx4 v[160:161], off
	v_lshl_add_u64 v[160:161], s[48:49], 0, v[138:139]
	s_add_i32 m0, s52, 0x2000
	s_nop 0
	global_load_lds_dwordx4 v[160:161], off
	v_lshl_add_u64 v[160:161], v[224:225], 0, s[18:19]
	s_mov_b32 m0, s66
	s_nop 0
	global_load_lds_dwordx4 v[160:161], off
	v_lshl_add_u64 v[160:161], v[226:227], 0, s[18:19]
	s_mov_b32 m0, s67
	s_nop 0
	global_load_lds_dwordx4 v[160:161], off
	s_waitcnt vmcnt(8)
	s_waitcnt lgkmcnt(0)
	s_barrier
	s_setprio 1
	s_waitcnt lgkmcnt(0)
	v_mfma_f32_16x16x32_bf16 v[62:65], v[130:133], v[190:193], v[62:65]
	v_mfma_f32_16x16x32_bf16 v[58:61], v[156:159], v[190:193], v[58:61]
	v_mfma_f32_16x16x32_bf16 v[46:49], v[130:133], v[198:201], v[46:49]
	v_mfma_f32_16x16x32_bf16 v[42:45], v[156:159], v[198:201], v[42:45]
	v_mfma_f32_16x16x32_bf16 v[30:33], v[130:133], v[206:209], v[30:33]
	v_mfma_f32_16x16x32_bf16 v[26:29], v[156:159], v[206:209], v[26:29]
	v_mfma_f32_16x16x32_bf16 v[14:17], v[130:133], v[214:217], v[14:17]
	v_mfma_f32_16x16x32_bf16 v[10:13], v[156:159], v[214:217], v[10:13]
	v_mfma_f32_16x16x32_bf16 v[62:65], v[134:137], v[194:197], v[62:65]
	v_mfma_f32_16x16x32_bf16 v[58:61], v[168:171], v[194:197], v[58:61]
	v_mfma_f32_16x16x32_bf16 v[46:49], v[134:137], v[202:205], v[46:49]
	v_mfma_f32_16x16x32_bf16 v[42:45], v[168:171], v[202:205], v[42:45]
	v_mfma_f32_16x16x32_bf16 v[30:33], v[134:137], v[210:213], v[30:33]
	v_mfma_f32_16x16x32_bf16 v[26:29], v[168:171], v[210:213], v[26:29]
	v_mfma_f32_16x16x32_bf16 v[14:17], v[134:137], v[218:221], v[14:17]
	v_mfma_f32_16x16x32_bf16 v[10:13], v[168:171], v[218:221], v[10:13]
	s_setprio 0
	s_setprio 1
	v_mfma_f32_16x16x32_bf16 v[54:57], v[172:175], v[190:193], v[54:57]
	v_mfma_f32_16x16x32_bf16 v[50:53], v[182:185], v[190:193], v[50:53]
	v_mfma_f32_16x16x32_bf16 v[38:41], v[172:175], v[198:201], v[38:41]
	v_mfma_f32_16x16x32_bf16 v[34:37], v[182:185], v[198:201], v[34:37]
	v_mfma_f32_16x16x32_bf16 v[22:25], v[172:175], v[206:209], v[22:25]
	v_mfma_f32_16x16x32_bf16 v[18:21], v[182:185], v[206:209], v[18:21]
	v_mfma_f32_16x16x32_bf16 v[6:9], v[172:175], v[214:217], v[6:9]
	v_mfma_f32_16x16x32_bf16 v[2:5], v[182:185], v[214:217], v[2:5]
	v_mfma_f32_16x16x32_bf16 v[54:57], v[178:181], v[194:197], v[54:57]
	v_mfma_f32_16x16x32_bf16 v[50:53], v[186:189], v[194:197], v[50:53]
	v_mfma_f32_16x16x32_bf16 v[38:41], v[178:181], v[202:205], v[38:41]
	v_mfma_f32_16x16x32_bf16 v[34:37], v[186:189], v[202:205], v[34:37]
	v_mfma_f32_16x16x32_bf16 v[22:25], v[178:181], v[210:213], v[22:25]
	v_mfma_f32_16x16x32_bf16 v[18:21], v[186:189], v[210:213], v[18:21]
	v_mfma_f32_16x16x32_bf16 v[6:9], v[178:181], v[218:221], v[6:9]
	v_mfma_f32_16x16x32_bf16 v[2:5], v[186:189], v[218:221], v[2:5]
	s_setprio 0
	s_add_i32 s79, s79, 2
	s_add_u32 s44, s44, 0x100
	s_addc_u32 s45, s45, 0
	s_add_u32 s75, s75, 0x100
	s_addc_u32 s78, s78, 0
	s_cmp_gt_u32 s79, 13
	s_barrier
	s_cbranch_scc0 .LBB0_783
	s_and_b64 vcc, exec, s[20:21]
	s_cbranch_vccz .LBB0_786
	s_barrier

.LBB0_803:
	ds_read_b128 v[130:133], v174
	ds_read_b128 v[134:137], v174 offset:1024
	ds_read_b128 v[138:141], v174 offset:2048
	ds_read_b128 v[142:145], v174 offset:3072
	ds_read_b128 v[164:167], v175
	ds_read_b128 v[168:171], v175 offset:1024
	ds_read_b128 v[178:181], v175 offset:2048
	ds_read_b128 v[182:185], v175 offset:3072
	s_add_u32 s42, s40, 0xfffc0080
	s_addc_u32 s43, s41, -1
	s_cmp_eq_u32 s67, 12
	s_cselect_b32 s45, s13, s43
	s_cselect_b32 s44, s21, s42
	s_cselect_b32 s43, s19, s66
	s_cselect_b32 s42, s64, s65
	v_lshl_add_u64 v[218:219], s[40:41], 0, v[156:157]
	s_add_i32 m0, s39, 0xc000
	ds_read_b128 v[186:189], v177
	ds_read_b128 v[190:193], v177 offset:1024
	ds_read_b128 v[194:197], v177 offset:2048
	ds_read_b128 v[198:201], v177 offset:3072
	ds_read_b128 v[202:205], v177 offset:4096
	ds_read_b128 v[206:209], v177 offset:5120
	ds_read_b128 v[210:213], v177 offset:6144
	ds_read_b128 v[214:217], v177 offset:7168
	global_load_lds_dwordx4 v[218:219], off
	v_lshl_add_u64 v[218:219], s[40:41], 0, v[158:159]
	s_add_i32 m0, s39, 0xe000
	s_nop 0
	global_load_lds_dwordx4 v[218:219], off
	s_waitcnt vmcnt(8)
	s_waitcnt lgkmcnt(0)
	s_barrier
	s_setprio 1
	s_waitcnt lgkmcnt(0)
	v_mfma_f32_16x16x32_bf16 v[126:129], v[130:133], v[186:189], v[126:129]
	v_mfma_f32_16x16x32_bf16 v[122:125], v[138:141], v[186:189], v[122:125]
	v_mfma_f32_16x16x32_bf16 v[110:113], v[130:133], v[194:197], v[110:113]
	v_mfma_f32_16x16x32_bf16 v[106:109], v[138:141], v[194:197], v[106:109]
	v_mfma_f32_16x16x32_bf16 v[94:97], v[130:133], v[202:205], v[94:97]
	v_mfma_f32_16x16x32_bf16 v[90:93], v[138:141], v[202:205], v[90:93]
	v_mfma_f32_16x16x32_bf16 v[78:81], v[130:133], v[210:213], v[78:81]
	v_mfma_f32_16x16x32_bf16 v[74:77], v[138:141], v[210:213], v[74:77]
	v_mfma_f32_16x16x32_bf16 v[126:129], v[134:137], v[190:193], v[126:129]
	v_mfma_f32_16x16x32_bf16 v[122:125], v[142:145], v[190:193], v[122:125]
	v_mfma_f32_16x16x32_bf16 v[110:113], v[134:137], v[198:201], v[110:113]
	v_mfma_f32_16x16x32_bf16 v[106:109], v[142:145], v[198:201], v[106:109]
	v_mfma_f32_16x16x32_bf16 v[94:97], v[134:137], v[206:209], v[94:97]
	v_mfma_f32_16x16x32_bf16 v[90:93], v[142:145], v[206:209], v[90:93]
	v_mfma_f32_16x16x32_bf16 v[78:81], v[134:137], v[214:217], v[78:81]
	v_mfma_f32_16x16x32_bf16 v[74:77], v[142:145], v[214:217], v[74:77]
	s_setprio 0
	s_setprio 1
	v_mfma_f32_16x16x32_bf16 v[118:121], v[164:167], v[186:189], v[118:121]
	v_mfma_f32_16x16x32_bf16 v[114:117], v[178:181], v[186:189], v[114:117]
	v_mfma_f32_16x16x32_bf16 v[102:105], v[164:167], v[194:197], v[102:105]
	v_mfma_f32_16x16x32_bf16 v[98:101], v[178:181], v[194:197], v[98:101]
	v_mfma_f32_16x16x32_bf16 v[86:89], v[164:167], v[202:205], v[86:89]
	v_mfma_f32_16x16x32_bf16 v[82:85], v[178:181], v[202:205], v[82:85]
	v_mfma_f32_16x16x32_bf16 v[70:73], v[164:167], v[210:213], v[70:73]
	v_mfma_f32_16x16x32_bf16 v[66:69], v[178:181], v[210:213], v[66:69]
	v_mfma_f32_16x16x32_bf16 v[118:121], v[168:171], v[190:193], v[118:121]
	v_mfma_f32_16x16x32_bf16 v[114:117], v[182:185], v[190:193], v[114:117]
	v_mfma_f32_16x16x32_bf16 v[102:105], v[168:171], v[198:201], v[102:105]
	v_mfma_f32_16x16x32_bf16 v[98:101], v[182:185], v[198:201], v[98:101]
	v_mfma_f32_16x16x32_bf16 v[86:89], v[168:171], v[206:209], v[86:89]
	v_mfma_f32_16x16x32_bf16 v[82:85], v[182:185], v[206:209], v[82:85]
	v_mfma_f32_16x16x32_bf16 v[70:73], v[168:171], v[214:217], v[70:73]
	v_mfma_f32_16x16x32_bf16 v[66:69], v[182:185], v[214:217], v[66:69]
	s_setprio 0
	s_barrier
	s_add_i32 s69, s62, s48
	v_lshl_add_u64 v[218:219], s[42:43], 0, v[152:153]
	s_mov_b32 m0, s69
	ds_read_b128 v[186:189], v177 offset:16384
	ds_read_b128 v[190:193], v177 offset:17408
	ds_read_b128 v[194:197], v177 offset:18432
	ds_read_b128 v[198:201], v177 offset:19456
	ds_read_b128 v[202:205], v177 offset:20480
	ds_read_b128 v[206:209], v177 offset:21504
	ds_read_b128 v[210:213], v177 offset:22528
	ds_read_b128 v[214:217], v177 offset:23552
	global_load_lds_dwordx4 v[218:219], off
	s_add_i32 m0, s69, 0x2000
	s_add_u32 s72, s42, 0x40000
	v_lshl_add_u64 v[220:221], s[42:43], 0, v[148:149]
	s_addc_u32 s73, s43, 0
	s_add_i32 s69, s63, s48
	global_load_lds_dwordx4 v[220:221], off
	v_lshl_add_u64 v[222:223], s[72:73], 0, v[152:153]
	s_mov_b32 m0, s69
	v_lshl_add_u64 v[224:225], s[44:45], 0, v[150:151]
	global_load_lds_dwordx4 v[222:223], off
	v_lshl_add_u64 v[222:223], s[72:73], 0, v[148:149]
	s_add_i32 m0, s69, 0x2000
	s_nop 0
	global_load_lds_dwordx4 v[222:223], off
	v_lshl_add_u64 v[222:223], s[44:45], 0, v[154:155]
	s_mov_b32 m0, s39
	s_nop 0
	global_load_lds_dwordx4 v[222:223], off
	s_mov_b32 m0, s56
	s_nop 0
	global_load_lds_dwordx4 v[224:225], off
	s_waitcnt vmcnt(8)
	s_waitcnt lgkmcnt(0)
	s_barrier
	s_setprio 1
	s_waitcnt lgkmcnt(0)
	v_mfma_f32_16x16x32_bf16 v[62:65], v[130:133], v[186:189], v[62:65]
	v_mfma_f32_16x16x32_bf16 v[58:61], v[138:141], v[186:189], v[58:61]
	v_mfma_f32_16x16x32_bf16 v[46:49], v[130:133], v[194:197], v[46:49]
	v_mfma_f32_16x16x32_bf16 v[42:45], v[138:141], v[194:197], v[42:45]
	v_mfma_f32_16x16x32_bf16 v[30:33], v[130:133], v[202:205], v[30:33]
	v_mfma_f32_16x16x32_bf16 v[26:29], v[138:141], v[202:205], v[26:29]
	v_mfma_f32_16x16x32_bf16 v[14:17], v[130:133], v[210:213], v[14:17]
	v_mfma_f32_16x16x32_bf16 v[10:13], v[138:141], v[210:213], v[10:13]
	v_mfma_f32_16x16x32_bf16 v[62:65], v[134:137], v[190:193], v[62:65]
	v_mfma_f32_16x16x32_bf16 v[58:61], v[142:145], v[190:193], v[58:61]
	v_mfma_f32_16x16x32_bf16 v[46:49], v[134:137], v[198:201], v[46:49]
	v_mfma_f32_16x16x32_bf16 v[42:45], v[142:145], v[198:201], v[42:45]
	v_mfma_f32_16x16x32_bf16 v[30:33], v[134:137], v[206:209], v[30:33]
	v_mfma_f32_16x16x32_bf16 v[26:29], v[142:145], v[206:209], v[26:29]
	v_mfma_f32_16x16x32_bf16 v[14:17], v[134:137], v[214:217], v[14:17]
	v_mfma_f32_16x16x32_bf16 v[10:13], v[142:145], v[214:217], v[10:13]
	s_setprio 0
	s_setprio 1
	v_mfma_f32_16x16x32_bf16 v[54:57], v[164:167], v[186:189], v[54:57]
	v_mfma_f32_16x16x32_bf16 v[50:53], v[178:181], v[186:189], v[50:53]
	v_mfma_f32_16x16x32_bf16 v[38:41], v[164:167], v[194:197], v[38:41]
	v_mfma_f32_16x16x32_bf16 v[34:37], v[178:181], v[194:197], v[34:37]
	v_mfma_f32_16x16x32_bf16 v[22:25], v[164:167], v[202:205], v[22:25]
	v_mfma_f32_16x16x32_bf16 v[18:21], v[178:181], v[202:205], v[18:21]
	v_mfma_f32_16x16x32_bf16 v[6:9], v[164:167], v[210:213], v[6:9]
	v_mfma_f32_16x16x32_bf16 v[2:5], v[178:181], v[210:213], v[2:5]
	v_mfma_f32_16x16x32_bf16 v[54:57], v[168:171], v[190:193], v[54:57]
	v_mfma_f32_16x16x32_bf16 v[50:53], v[182:185], v[190:193], v[50:53]
	v_mfma_f32_16x16x32_bf16 v[38:41], v[168:171], v[198:201], v[38:41]
	v_mfma_f32_16x16x32_bf16 v[34:37], v[182:185], v[198:201], v[34:37]
	v_mfma_f32_16x16x32_bf16 v[22:25], v[168:171], v[206:209], v[22:25]
	v_mfma_f32_16x16x32_bf16 v[18:21], v[182:185], v[206:209], v[18:21]
	v_mfma_f32_16x16x32_bf16 v[6:9], v[168:171], v[214:217], v[6:9]
	v_mfma_f32_16x16x32_bf16 v[2:5], v[182:185], v[214:217], v[2:5]
	s_setprio 0
	s_barrier
	s_add_i32 s69, 0, 0x18000
	s_add_i32 s72, 0, 0x1c000
	v_add_u32_e32 v142, s69, v172
	v_add_u32_e32 v182, s72, v172
	ds_read_b128 v[130:133], v142
	ds_read_b128 v[134:137], v142 offset:1024
	ds_read_b128 v[138:141], v142 offset:2048
	ds_read_b128 v[142:145], v142 offset:3072
	ds_read_b128 v[164:167], v182
	ds_read_b128 v[168:171], v182 offset:1024
	ds_read_b128 v[178:181], v182 offset:2048
	ds_read_b128 v[182:185], v182 offset:3072
	s_add_u32 s44, s44, 0x40000
	s_addc_u32 s45, s45, 0
	s_mov_b32 m0, s57
	v_lshl_add_u64 v[226:227], s[44:45], 0, v[154:155]
	ds_read_b128 v[186:189], v177 offset:32768
	ds_read_b128 v[190:193], v177 offset:33792
	ds_read_b128 v[194:197], v177 offset:34816
	ds_read_b128 v[198:201], v177 offset:35840
	ds_read_b128 v[202:205], v177 offset:36864
	ds_read_b128 v[206:209], v177 offset:37888
	ds_read_b128 v[210:213], v177 offset:38912
	ds_read_b128 v[214:217], v177 offset:39936
	global_load_lds_dwordx4 v[226:227], off
	v_lshl_add_u64 v[226:227], s[44:45], 0, v[150:151]
	s_mov_b32 m0, s58
	s_nop 0
	global_load_lds_dwordx4 v[226:227], off
	s_waitcnt vmcnt(8)
	s_waitcnt lgkmcnt(0)
	s_barrier
	s_setprio 1
	s_waitcnt lgkmcnt(0)
	v_mfma_f32_16x16x32_bf16 v[126:129], v[130:133], v[186:189], v[126:129]
	v_mfma_f32_16x16x32_bf16 v[122:125], v[138:141], v[186:189], v[122:125]
	v_mfma_f32_16x16x32_bf16 v[110:113], v[130:133], v[194:197], v[110:113]
	v_mfma_f32_16x16x32_bf16 v[106:109], v[138:141], v[194:197], v[106:109]
	v_mfma_f32_16x16x32_bf16 v[94:97], v[130:133], v[202:205], v[94:97]
	v_mfma_f32_16x16x32_bf16 v[90:93], v[138:141], v[202:205], v[90:93]
	v_mfma_f32_16x16x32_bf16 v[78:81], v[130:133], v[210:213], v[78:81]
	v_mfma_f32_16x16x32_bf16 v[74:77], v[138:141], v[210:213], v[74:77]
	v_mfma_f32_16x16x32_bf16 v[126:129], v[134:137], v[190:193], v[126:129]
	v_mfma_f32_16x16x32_bf16 v[122:125], v[142:145], v[190:193], v[122:125]
	v_mfma_f32_16x16x32_bf16 v[110:113], v[134:137], v[198:201], v[110:113]
	v_mfma_f32_16x16x32_bf16 v[106:109], v[142:145], v[198:201], v[106:109]
	v_mfma_f32_16x16x32_bf16 v[94:97], v[134:137], v[206:209], v[94:97]
	v_mfma_f32_16x16x32_bf16 v[90:93], v[142:145], v[206:209], v[90:93]
	v_mfma_f32_16x16x32_bf16 v[78:81], v[134:137], v[214:217], v[78:81]
	v_mfma_f32_16x16x32_bf16 v[74:77], v[142:145], v[214:217], v[74:77]
	s_setprio 0
	s_setprio 1
	v_mfma_f32_16x16x32_bf16 v[118:121], v[164:167], v[186:189], v[118:121]
	v_mfma_f32_16x16x32_bf16 v[114:117], v[178:181], v[186:189], v[114:117]
	v_mfma_f32_16x16x32_bf16 v[102:105], v[164:167], v[194:197], v[102:105]
	v_mfma_f32_16x16x32_bf16 v[98:101], v[178:181], v[194:197], v[98:101]
	v_mfma_f32_16x16x32_bf16 v[86:89], v[164:167], v[202:205], v[86:89]
	v_mfma_f32_16x16x32_bf16 v[82:85], v[178:181], v[202:205], v[82:85]
	v_mfma_f32_16x16x32_bf16 v[70:73], v[164:167], v[210:213], v[70:73]
	v_mfma_f32_16x16x32_bf16 v[66:69], v[178:181], v[210:213], v[66:69]
	v_mfma_f32_16x16x32_bf16 v[118:121], v[168:171], v[190:193], v[118:121]
	v_mfma_f32_16x16x32_bf16 v[114:117], v[182:185], v[190:193], v[114:117]
	v_mfma_f32_16x16x32_bf16 v[102:105], v[168:171], v[198:201], v[102:105]
	v_mfma_f32_16x16x32_bf16 v[98:101], v[182:185], v[198:201], v[98:101]
	v_mfma_f32_16x16x32_bf16 v[86:89], v[168:171], v[206:209], v[86:89]
	v_mfma_f32_16x16x32_bf16 v[82:85], v[182:185], v[206:209], v[82:85]
	v_mfma_f32_16x16x32_bf16 v[70:73], v[168:171], v[214:217], v[70:73]
	v_mfma_f32_16x16x32_bf16 v[66:69], v[182:185], v[214:217], v[66:69]
	s_setprio 0
	s_barrier
	s_add_i32 s44, s69, s48
	v_lshl_add_u64 v[218:219], v[218:219], 0, s[10:11]
	s_mov_b32 m0, s44
	ds_read_b128 v[186:189], v177 offset:49152
	ds_read_b128 v[190:193], v177 offset:50176
	ds_read_b128 v[194:197], v177 offset:51200
	ds_read_b128 v[198:201], v177 offset:52224
	ds_read_b128 v[202:205], v177 offset:53248
	ds_read_b128 v[206:209], v177 offset:54272
	ds_read_b128 v[210:213], v177 offset:55296
	ds_read_b128 v[214:217], v177 offset:56320
	global_load_lds_dwordx4 v[218:219], off
	s_add_i32 m0, s44, 0x2000
	s_add_u32 s42, s42, 0x40080
	v_lshl_add_u64 v[218:219], v[220:221], 0, s[10:11]
	s_addc_u32 s43, s43, 0
	s_add_i32 s44, s72, s48
	global_load_lds_dwordx4 v[218:219], off
	v_lshl_add_u64 v[218:219], s[42:43], 0, v[152:153]
	s_mov_b32 m0, s44
	s_nop 0
	global_load_lds_dwordx4 v[218:219], off
	v_lshl_add_u64 v[218:219], s[42:43], 0, v[148:149]
	s_add_i32 m0, s44, 0x2000
	s_nop 0
	global_load_lds_dwordx4 v[218:219], off
	v_lshl_add_u64 v[218:219], v[222:223], 0, s[10:11]
	s_mov_b32 m0, s60
	s_nop 0
	global_load_lds_dwordx4 v[218:219], off
	v_lshl_add_u64 v[218:219], v[224:225], 0, s[10:11]
	s_mov_b32 m0, s61
	s_nop 0
	global_load_lds_dwordx4 v[218:219], off
	s_waitcnt vmcnt(8)
	s_waitcnt lgkmcnt(0)
	s_barrier
	s_setprio 1
	s_waitcnt lgkmcnt(0)
	v_mfma_f32_16x16x32_bf16 v[62:65], v[130:133], v[186:189], v[62:65]
	v_mfma_f32_16x16x32_bf16 v[58:61], v[138:141], v[186:189], v[58:61]
	v_mfma_f32_16x16x32_bf16 v[46:49], v[130:133], v[194:197], v[46:49]
	v_mfma_f32_16x16x32_bf16 v[42:45], v[138:141], v[194:197], v[42:45]
	v_mfma_f32_16x16x32_bf16 v[30:33], v[130:133], v[202:205], v[30:33]
	v_mfma_f32_16x16x32_bf16 v[26:29], v[138:141], v[202:205], v[26:29]
	v_mfma_f32_16x16x32_bf16 v[14:17], v[130:133], v[210:213], v[14:17]
	v_mfma_f32_16x16x32_bf16 v[10:13], v[138:141], v[210:213], v[10:13]
	v_mfma_f32_16x16x32_bf16 v[62:65], v[134:137], v[190:193], v[62:65]
	v_mfma_f32_16x16x32_bf16 v[58:61], v[142:145], v[190:193], v[58:61]
	v_mfma_f32_16x16x32_bf16 v[46:49], v[134:137], v[198:201], v[46:49]
	v_mfma_f32_16x16x32_bf16 v[42:45], v[142:145], v[198:201], v[42:45]
	v_mfma_f32_16x16x32_bf16 v[30:33], v[134:137], v[206:209], v[30:33]
	v_mfma_f32_16x16x32_bf16 v[26:29], v[142:145], v[206:209], v[26:29]
	v_mfma_f32_16x16x32_bf16 v[14:17], v[134:137], v[214:217], v[14:17]
	v_mfma_f32_16x16x32_bf16 v[10:13], v[142:145], v[214:217], v[10:13]
	s_setprio 0
	s_setprio 1
	v_mfma_f32_16x16x32_bf16 v[54:57], v[164:167], v[186:189], v[54:57]
	v_mfma_f32_16x16x32_bf16 v[50:53], v[178:181], v[186:189], v[50:53]
	v_mfma_f32_16x16x32_bf16 v[38:41], v[164:167], v[194:197], v[38:41]
	v_mfma_f32_16x16x32_bf16 v[34:37], v[178:181], v[194:197], v[34:37]
	v_mfma_f32_16x16x32_bf16 v[22:25], v[164:167], v[202:205], v[22:25]
	v_mfma_f32_16x16x32_bf16 v[18:21], v[178:181], v[202:205], v[18:21]
	v_mfma_f32_16x16x32_bf16 v[6:9], v[164:167], v[210:213], v[6:9]
	v_mfma_f32_16x16x32_bf16 v[2:5], v[178:181], v[210:213], v[2:5]
	v_mfma_f32_16x16x32_bf16 v[54:57], v[168:171], v[190:193], v[54:57]
	v_mfma_f32_16x16x32_bf16 v[50:53], v[182:185], v[190:193], v[50:53]
	v_mfma_f32_16x16x32_bf16 v[38:41], v[168:171], v[198:201], v[38:41]
	v_mfma_f32_16x16x32_bf16 v[34:37], v[182:185], v[198:201], v[34:37]
	v_mfma_f32_16x16x32_bf16 v[22:25], v[168:171], v[206:209], v[22:25]
	v_mfma_f32_16x16x32_bf16 v[18:21], v[182:185], v[206:209], v[18:21]
	v_mfma_f32_16x16x32_bf16 v[6:9], v[168:171], v[214:217], v[6:9]
	v_mfma_f32_16x16x32_bf16 v[2:5], v[182:185], v[214:217], v[2:5]
	s_setprio 0
	s_add_i32 s67, s67, 2
	s_add_u32 s40, s40, 0x100
	s_addc_u32 s41, s41, 0
	s_add_u32 s65, s65, 0x100
	s_addc_u32 s66, s66, 0
	s_cmp_gt_u32 s67, 13
	s_barrier
	s_cbranch_scc0 .LBB0_803
	s_and_b64 vcc, exec, s[16:17]
	s_cbranch_vccz .LBB0_806
	s_barrier

.LBB0_890:
	ds_read_b128 v[142:145], v166
	ds_read_b128 v[148:151], v166 offset:1024
	ds_read_b128 v[152:155], v166 offset:2048
	ds_read_b128 v[156:159], v166 offset:3072
	ds_read_b128 v[160:163], v167
	ds_read_b128 v[172:175], v167 offset:1024
	ds_read_b128 v[178:181], v167 offset:2048
	ds_read_b128 v[182:185], v167 offset:3072
	s_add_u32 s42, s40, 0xfff80080
	s_addc_u32 s43, s41, -1
	s_cmp_eq_u32 s82, 28
	s_cselect_b32 s45, s13, s43
	s_cselect_b32 s44, s21, s42
	s_cselect_b32 s43, s19, s81
	s_cselect_b32 s42, s74, s75
	v_lshl_add_u64 v[218:219], s[40:41], 0, v[134:135]
	s_add_i32 m0, s39, 0xc000
	ds_read_b128 v[186:189], v168
	ds_read_b128 v[190:193], v168 offset:1024
	ds_read_b128 v[194:197], v168 offset:2048
	ds_read_b128 v[198:201], v168 offset:3072
	ds_read_b128 v[202:205], v168 offset:4096
	ds_read_b128 v[206:209], v168 offset:5120
	ds_read_b128 v[210:213], v168 offset:6144
	ds_read_b128 v[214:217], v168 offset:7168
	global_load_lds_dwordx4 v[218:219], off
	v_lshl_add_u64 v[218:219], s[40:41], 0, v[136:137]
	s_add_i32 m0, s39, 0xe000
	s_nop 0
	global_load_lds_dwordx4 v[218:219], off
	s_waitcnt vmcnt(8)
	s_waitcnt lgkmcnt(0)
	s_barrier
	s_setprio 1
	s_waitcnt lgkmcnt(0)
	v_mfma_f32_16x16x32_bf16 v[122:125], v[142:145], v[186:189], v[122:125]
	v_mfma_f32_16x16x32_bf16 v[126:129], v[152:155], v[186:189], v[126:129]
	v_mfma_f32_16x16x32_bf16 v[114:117], v[142:145], v[194:197], v[114:117]
	v_mfma_f32_16x16x32_bf16 v[118:121], v[152:155], v[194:197], v[118:121]
	v_mfma_f32_16x16x32_bf16 v[94:97], v[142:145], v[202:205], v[94:97]
	v_mfma_f32_16x16x32_bf16 v[90:93], v[152:155], v[202:205], v[90:93]
	v_mfma_f32_16x16x32_bf16 v[86:89], v[142:145], v[210:213], v[86:89]
	v_mfma_f32_16x16x32_bf16 v[82:85], v[152:155], v[210:213], v[82:85]
	v_mfma_f32_16x16x32_bf16 v[122:125], v[148:151], v[190:193], v[122:125]
	v_mfma_f32_16x16x32_bf16 v[126:129], v[156:159], v[190:193], v[126:129]
	v_mfma_f32_16x16x32_bf16 v[114:117], v[148:151], v[198:201], v[114:117]
	v_mfma_f32_16x16x32_bf16 v[118:121], v[156:159], v[198:201], v[118:121]
	v_mfma_f32_16x16x32_bf16 v[94:97], v[148:151], v[206:209], v[94:97]
	v_mfma_f32_16x16x32_bf16 v[90:93], v[156:159], v[206:209], v[90:93]
	v_mfma_f32_16x16x32_bf16 v[86:89], v[148:151], v[214:217], v[86:89]
	v_mfma_f32_16x16x32_bf16 v[82:85], v[156:159], v[214:217], v[82:85]
	s_setprio 0
	s_setprio 1
	v_mfma_f32_16x16x32_bf16 v[110:113], v[160:163], v[186:189], v[110:113]
	v_mfma_f32_16x16x32_bf16 v[106:109], v[178:181], v[186:189], v[106:109]
	v_mfma_f32_16x16x32_bf16 v[102:105], v[160:163], v[194:197], v[102:105]
	v_mfma_f32_16x16x32_bf16 v[98:101], v[178:181], v[194:197], v[98:101]
	v_mfma_f32_16x16x32_bf16 v[78:81], v[160:163], v[202:205], v[78:81]
	v_mfma_f32_16x16x32_bf16 v[74:77], v[178:181], v[202:205], v[74:77]
	v_mfma_f32_16x16x32_bf16 v[70:73], v[160:163], v[210:213], v[70:73]
	v_mfma_f32_16x16x32_bf16 v[66:69], v[178:181], v[210:213], v[66:69]
	v_mfma_f32_16x16x32_bf16 v[110:113], v[172:175], v[190:193], v[110:113]
	v_mfma_f32_16x16x32_bf16 v[106:109], v[182:185], v[190:193], v[106:109]
	v_mfma_f32_16x16x32_bf16 v[102:105], v[172:175], v[198:201], v[102:105]
	v_mfma_f32_16x16x32_bf16 v[98:101], v[182:185], v[198:201], v[98:101]
	v_mfma_f32_16x16x32_bf16 v[78:81], v[172:175], v[206:209], v[78:81]
	v_mfma_f32_16x16x32_bf16 v[74:77], v[182:185], v[206:209], v[74:77]
	v_mfma_f32_16x16x32_bf16 v[70:73], v[172:175], v[214:217], v[70:73]
	v_mfma_f32_16x16x32_bf16 v[66:69], v[182:185], v[214:217], v[66:69]
	s_setprio 0
	s_barrier
	s_add_i32 s72, s63, s53
	v_lshl_add_u64 v[218:219], s[42:43], 0, v[132:133]
	s_mov_b32 m0, s72
	ds_read_b128 v[186:189], v168 offset:16384
	ds_read_b128 v[190:193], v168 offset:17408
	ds_read_b128 v[194:197], v168 offset:18432
	ds_read_b128 v[198:201], v168 offset:19456
	ds_read_b128 v[202:205], v168 offset:20480
	ds_read_b128 v[206:209], v168 offset:21504
	ds_read_b128 v[210:213], v168 offset:22528
	ds_read_b128 v[214:217], v168 offset:23552
	global_load_lds_dwordx4 v[218:219], off
	s_add_i32 m0, s72, 0x2000
	s_add_u32 s72, s42, 0x80000
	v_lshl_add_u64 v[220:221], s[42:43], 0, v[130:131]
	s_addc_u32 s73, s43, 0
	s_add_i32 s83, s64, s53
	global_load_lds_dwordx4 v[220:221], off
	v_lshl_add_u64 v[222:223], s[72:73], 0, v[132:133]
	s_mov_b32 m0, s83
	v_lshl_add_u64 v[224:225], s[44:45], 0, v[130:131]
	global_load_lds_dwordx4 v[222:223], off
	v_lshl_add_u64 v[222:223], s[72:73], 0, v[130:131]
	s_add_i32 m0, s83, 0x2000
	s_nop 0
	global_load_lds_dwordx4 v[222:223], off
	v_lshl_add_u64 v[222:223], s[44:45], 0, v[132:133]
	s_mov_b32 m0, s39
	s_nop 0
	global_load_lds_dwordx4 v[222:223], off
	s_mov_b32 m0, s55
	s_nop 0
	global_load_lds_dwordx4 v[224:225], off
	s_waitcnt vmcnt(8)
	s_waitcnt lgkmcnt(0)
	s_barrier
	s_setprio 1
	s_waitcnt lgkmcnt(0)
	v_mfma_f32_16x16x32_bf16 v[62:65], v[142:145], v[186:189], v[62:65]
	v_mfma_f32_16x16x32_bf16 v[58:61], v[152:155], v[186:189], v[58:61]
	v_mfma_f32_16x16x32_bf16 v[54:57], v[142:145], v[194:197], v[54:57]
	v_mfma_f32_16x16x32_bf16 v[50:53], v[152:155], v[194:197], v[50:53]
	v_mfma_f32_16x16x32_bf16 v[30:33], v[142:145], v[202:205], v[30:33]
	v_mfma_f32_16x16x32_bf16 v[26:29], v[152:155], v[202:205], v[26:29]
	v_mfma_f32_16x16x32_bf16 v[22:25], v[142:145], v[210:213], v[22:25]
	v_mfma_f32_16x16x32_bf16 v[18:21], v[152:155], v[210:213], v[18:21]
	v_mfma_f32_16x16x32_bf16 v[62:65], v[148:151], v[190:193], v[62:65]
	v_mfma_f32_16x16x32_bf16 v[58:61], v[156:159], v[190:193], v[58:61]
	v_mfma_f32_16x16x32_bf16 v[54:57], v[148:151], v[198:201], v[54:57]
	v_mfma_f32_16x16x32_bf16 v[50:53], v[156:159], v[198:201], v[50:53]
	v_mfma_f32_16x16x32_bf16 v[30:33], v[148:151], v[206:209], v[30:33]
	v_mfma_f32_16x16x32_bf16 v[26:29], v[156:159], v[206:209], v[26:29]
	v_mfma_f32_16x16x32_bf16 v[22:25], v[148:151], v[214:217], v[22:25]
	v_mfma_f32_16x16x32_bf16 v[18:21], v[156:159], v[214:217], v[18:21]
	s_setprio 0
	s_setprio 1
	v_mfma_f32_16x16x32_bf16 v[46:49], v[160:163], v[186:189], v[46:49]
	v_mfma_f32_16x16x32_bf16 v[42:45], v[178:181], v[186:189], v[42:45]
	v_mfma_f32_16x16x32_bf16 v[38:41], v[160:163], v[194:197], v[38:41]
	v_mfma_f32_16x16x32_bf16 v[34:37], v[178:181], v[194:197], v[34:37]
	v_mfma_f32_16x16x32_bf16 v[14:17], v[160:163], v[202:205], v[14:17]
	v_mfma_f32_16x16x32_bf16 v[10:13], v[178:181], v[202:205], v[10:13]
	v_mfma_f32_16x16x32_bf16 v[6:9], v[160:163], v[210:213], v[6:9]
	v_mfma_f32_16x16x32_bf16 v[2:5], v[178:181], v[210:213], v[2:5]
	v_mfma_f32_16x16x32_bf16 v[46:49], v[172:175], v[190:193], v[46:49]
	v_mfma_f32_16x16x32_bf16 v[42:45], v[182:185], v[190:193], v[42:45]
	v_mfma_f32_16x16x32_bf16 v[38:41], v[172:175], v[198:201], v[38:41]
	v_mfma_f32_16x16x32_bf16 v[34:37], v[182:185], v[198:201], v[34:37]
	v_mfma_f32_16x16x32_bf16 v[14:17], v[172:175], v[206:209], v[14:17]
	v_mfma_f32_16x16x32_bf16 v[10:13], v[182:185], v[206:209], v[10:13]
	v_mfma_f32_16x16x32_bf16 v[6:9], v[172:175], v[214:217], v[6:9]
	v_mfma_f32_16x16x32_bf16 v[2:5], v[182:185], v[214:217], v[2:5]
	s_setprio 0
	s_barrier
	s_add_i32 s72, 0, 0x18000
	s_add_i32 s73, 0, 0x1c000
	v_add_u32_e32 v156, s72, v164
	v_add_u32_e32 v171, s73, v164
	ds_read_b128 v[142:145], v156
	ds_read_b128 v[148:151], v156 offset:1024
	ds_read_b128 v[152:155], v156 offset:2048
	ds_read_b128 v[156:159], v156 offset:3072
	ds_read_b128 v[160:163], v171
	ds_read_b128 v[172:175], v171 offset:1024
	ds_read_b128 v[178:181], v171 offset:2048
	ds_read_b128 v[182:185], v171 offset:3072
	s_add_u32 s44, s44, 0x80000
	s_addc_u32 s45, s45, 0
	s_mov_b32 m0, s56
	v_lshl_add_u64 v[226:227], s[44:45], 0, v[132:133]
	ds_read_b128 v[186:189], v168 offset:32768
	ds_read_b128 v[190:193], v168 offset:33792
	ds_read_b128 v[194:197], v168 offset:34816
	ds_read_b128 v[198:201], v168 offset:35840
	ds_read_b128 v[202:205], v168 offset:36864
	ds_read_b128 v[206:209], v168 offset:37888
	ds_read_b128 v[210:213], v168 offset:38912
	ds_read_b128 v[214:217], v168 offset:39936
	global_load_lds_dwordx4 v[226:227], off
	v_lshl_add_u64 v[226:227], s[44:45], 0, v[130:131]
	s_mov_b32 m0, s57
	s_nop 0
	global_load_lds_dwordx4 v[226:227], off
	s_waitcnt vmcnt(8)
	s_waitcnt lgkmcnt(0)
	s_barrier
	s_setprio 1
	s_waitcnt lgkmcnt(0)
	v_mfma_f32_16x16x32_bf16 v[122:125], v[142:145], v[186:189], v[122:125]
	v_mfma_f32_16x16x32_bf16 v[126:129], v[152:155], v[186:189], v[126:129]
	v_mfma_f32_16x16x32_bf16 v[114:117], v[142:145], v[194:197], v[114:117]
	v_mfma_f32_16x16x32_bf16 v[118:121], v[152:155], v[194:197], v[118:121]
	v_mfma_f32_16x16x32_bf16 v[94:97], v[142:145], v[202:205], v[94:97]
	v_mfma_f32_16x16x32_bf16 v[90:93], v[152:155], v[202:205], v[90:93]
	v_mfma_f32_16x16x32_bf16 v[86:89], v[142:145], v[210:213], v[86:89]
	v_mfma_f32_16x16x32_bf16 v[82:85], v[152:155], v[210:213], v[82:85]
	v_mfma_f32_16x16x32_bf16 v[122:125], v[148:151], v[190:193], v[122:125]
	v_mfma_f32_16x16x32_bf16 v[126:129], v[156:159], v[190:193], v[126:129]
	v_mfma_f32_16x16x32_bf16 v[114:117], v[148:151], v[198:201], v[114:117]
	v_mfma_f32_16x16x32_bf16 v[118:121], v[156:159], v[198:201], v[118:121]
	v_mfma_f32_16x16x32_bf16 v[94:97], v[148:151], v[206:209], v[94:97]
	v_mfma_f32_16x16x32_bf16 v[90:93], v[156:159], v[206:209], v[90:93]
	v_mfma_f32_16x16x32_bf16 v[86:89], v[148:151], v[214:217], v[86:89]
	v_mfma_f32_16x16x32_bf16 v[82:85], v[156:159], v[214:217], v[82:85]
	s_setprio 0
	s_setprio 1
	v_mfma_f32_16x16x32_bf16 v[110:113], v[160:163], v[186:189], v[110:113]
	v_mfma_f32_16x16x32_bf16 v[106:109], v[178:181], v[186:189], v[106:109]
	v_mfma_f32_16x16x32_bf16 v[102:105], v[160:163], v[194:197], v[102:105]
	v_mfma_f32_16x16x32_bf16 v[98:101], v[178:181], v[194:197], v[98:101]
	v_mfma_f32_16x16x32_bf16 v[78:81], v[160:163], v[202:205], v[78:81]
	v_mfma_f32_16x16x32_bf16 v[74:77], v[178:181], v[202:205], v[74:77]
	v_mfma_f32_16x16x32_bf16 v[70:73], v[160:163], v[210:213], v[70:73]
	v_mfma_f32_16x16x32_bf16 v[66:69], v[178:181], v[210:213], v[66:69]
	v_mfma_f32_16x16x32_bf16 v[110:113], v[172:175], v[190:193], v[110:113]
	v_mfma_f32_16x16x32_bf16 v[106:109], v[182:185], v[190:193], v[106:109]
	v_mfma_f32_16x16x32_bf16 v[102:105], v[172:175], v[198:201], v[102:105]
	v_mfma_f32_16x16x32_bf16 v[98:101], v[182:185], v[198:201], v[98:101]
	v_mfma_f32_16x16x32_bf16 v[78:81], v[172:175], v[206:209], v[78:81]
	v_mfma_f32_16x16x32_bf16 v[74:77], v[182:185], v[206:209], v[74:77]
	v_mfma_f32_16x16x32_bf16 v[70:73], v[172:175], v[214:217], v[70:73]
	v_mfma_f32_16x16x32_bf16 v[66:69], v[182:185], v[214:217], v[66:69]
	s_setprio 0
	s_barrier
	s_add_i32 s44, s72, s53
	v_lshl_add_u64 v[218:219], v[218:219], 0, s[8:9]
	s_mov_b32 m0, s44
	ds_read_b128 v[186:189], v168 offset:49152
	ds_read_b128 v[190:193], v168 offset:50176
	ds_read_b128 v[194:197], v168 offset:51200
	ds_read_b128 v[198:201], v168 offset:52224
	ds_read_b128 v[202:205], v168 offset:53248
	ds_read_b128 v[206:209], v168 offset:54272
	ds_read_b128 v[210:213], v168 offset:55296
	ds_read_b128 v[214:217], v168 offset:56320
	global_load_lds_dwordx4 v[218:219], off
	s_add_i32 m0, s44, 0x2000
	s_add_u32 s42, s42, 0x80080
	v_lshl_add_u64 v[218:219], v[220:221], 0, s[8:9]
	s_addc_u32 s43, s43, 0
	s_add_i32 s44, s73, s53
	global_load_lds_dwordx4 v[218:219], off
	v_lshl_add_u64 v[218:219], s[42:43], 0, v[132:133]
	s_mov_b32 m0, s44
	s_nop 0
	global_load_lds_dwordx4 v[218:219], off
	v_lshl_add_u64 v[218:219], s[42:43], 0, v[130:131]
	s_add_i32 m0, s44, 0x2000
	s_nop 0
	global_load_lds_dwordx4 v[218:219], off
	v_lshl_add_u64 v[218:219], v[222:223], 0, s[8:9]
	s_mov_b32 m0, s61
	s_nop 0
	global_load_lds_dwordx4 v[218:219], off
	v_lshl_add_u64 v[218:219], v[224:225], 0, s[8:9]
	s_mov_b32 m0, s62
	s_nop 0
	global_load_lds_dwordx4 v[218:219], off
	s_waitcnt vmcnt(8)
	s_waitcnt lgkmcnt(0)
	s_barrier
	s_setprio 1
	s_waitcnt lgkmcnt(0)
	v_mfma_f32_16x16x32_bf16 v[62:65], v[142:145], v[186:189], v[62:65]
	v_mfma_f32_16x16x32_bf16 v[58:61], v[152:155], v[186:189], v[58:61]
	v_mfma_f32_16x16x32_bf16 v[54:57], v[142:145], v[194:197], v[54:57]
	v_mfma_f32_16x16x32_bf16 v[50:53], v[152:155], v[194:197], v[50:53]
	v_mfma_f32_16x16x32_bf16 v[30:33], v[142:145], v[202:205], v[30:33]
	v_mfma_f32_16x16x32_bf16 v[26:29], v[152:155], v[202:205], v[26:29]
	v_mfma_f32_16x16x32_bf16 v[22:25], v[142:145], v[210:213], v[22:25]
	v_mfma_f32_16x16x32_bf16 v[18:21], v[152:155], v[210:213], v[18:21]
	v_mfma_f32_16x16x32_bf16 v[62:65], v[148:151], v[190:193], v[62:65]
	v_mfma_f32_16x16x32_bf16 v[58:61], v[156:159], v[190:193], v[58:61]
	v_mfma_f32_16x16x32_bf16 v[54:57], v[148:151], v[198:201], v[54:57]
	v_mfma_f32_16x16x32_bf16 v[50:53], v[156:159], v[198:201], v[50:53]
	v_mfma_f32_16x16x32_bf16 v[30:33], v[148:151], v[206:209], v[30:33]
	v_mfma_f32_16x16x32_bf16 v[26:29], v[156:159], v[206:209], v[26:29]
	v_mfma_f32_16x16x32_bf16 v[22:25], v[148:151], v[214:217], v[22:25]
	v_mfma_f32_16x16x32_bf16 v[18:21], v[156:159], v[214:217], v[18:21]
	s_setprio 0
	s_setprio 1
	v_mfma_f32_16x16x32_bf16 v[46:49], v[160:163], v[186:189], v[46:49]
	v_mfma_f32_16x16x32_bf16 v[42:45], v[178:181], v[186:189], v[42:45]
	v_mfma_f32_16x16x32_bf16 v[38:41], v[160:163], v[194:197], v[38:41]
	v_mfma_f32_16x16x32_bf16 v[34:37], v[178:181], v[194:197], v[34:37]
	v_mfma_f32_16x16x32_bf16 v[14:17], v[160:163], v[202:205], v[14:17]
	v_mfma_f32_16x16x32_bf16 v[10:13], v[178:181], v[202:205], v[10:13]
	v_mfma_f32_16x16x32_bf16 v[6:9], v[160:163], v[210:213], v[6:9]
	v_mfma_f32_16x16x32_bf16 v[2:5], v[178:181], v[210:213], v[2:5]
	v_mfma_f32_16x16x32_bf16 v[46:49], v[172:175], v[190:193], v[46:49]
	v_mfma_f32_16x16x32_bf16 v[42:45], v[182:185], v[190:193], v[42:45]
	v_mfma_f32_16x16x32_bf16 v[38:41], v[172:175], v[198:201], v[38:41]
	v_mfma_f32_16x16x32_bf16 v[34:37], v[182:185], v[198:201], v[34:37]
	v_mfma_f32_16x16x32_bf16 v[14:17], v[172:175], v[206:209], v[14:17]
	v_mfma_f32_16x16x32_bf16 v[10:13], v[182:185], v[206:209], v[10:13]
	v_mfma_f32_16x16x32_bf16 v[6:9], v[172:175], v[214:217], v[6:9]
	v_mfma_f32_16x16x32_bf16 v[2:5], v[182:185], v[214:217], v[2:5]
	s_setprio 0
	s_add_i32 s82, s82, 2
	s_add_u32 s40, s40, 0x100
	s_addc_u32 s41, s41, 0
	s_add_u32 s75, s75, 0x100
	s_addc_u32 s81, s81, 0
	s_cmp_gt_u32 s82, 29
	s_barrier
	s_cbranch_scc0 .LBB0_890
	s_and_b64 vcc, exec, s[16:17]
	s_cbranch_vccz .LBB0_893
	s_barrier

.LBB0_1043:
	ds_read_b128 v[154:157], v150
	ds_read_b128 v[158:161], v150 offset:1024
	ds_read_b128 v[162:165], v150 offset:2048
	ds_read_b128 v[166:169], v150 offset:3072
	ds_read_b128 v[170:173], v151
	ds_read_b128 v[178:181], v151 offset:1024
	ds_read_b128 v[182:185], v151 offset:2048
	ds_read_b128 v[186:189], v151 offset:3072
	s_add_u32 s38, s36, 0xfff80080
	s_addc_u32 s39, s37, -1
	s_cmp_eq_u32 s63, 28
	s_cselect_b32 s41, s13, s39
	s_cselect_b32 s40, s19, s38
	s_cselect_b32 s39, s17, s62
	s_cselect_b32 s38, s60, s61
	v_lshl_add_u64 v[174:175], s[36:37], 0, v[138:139]
	s_add_i32 m0, s25, 0xc000
	ds_read_b128 v[190:193], v152
	ds_read_b128 v[194:197], v152 offset:1024
	ds_read_b128 v[198:201], v152 offset:2048
	ds_read_b128 v[202:205], v152 offset:3072
	ds_read_b128 v[206:209], v152 offset:4096
	ds_read_b128 v[210:213], v152 offset:5120
	ds_read_b128 v[214:217], v152 offset:6144
	ds_read_b128 v[218:221], v152 offset:7168
	global_load_lds_dwordx4 v[174:175], off
	v_lshl_add_u64 v[174:175], s[36:37], 0, v[140:141]
	s_add_i32 m0, s25, 0xe000
	s_nop 0
	global_load_lds_dwordx4 v[174:175], off
	s_waitcnt vmcnt(8)
	s_waitcnt lgkmcnt(0)
	s_barrier
	s_setprio 1
	s_waitcnt lgkmcnt(0)
	v_mfma_f32_16x16x32_bf16 v[126:129], v[154:157], v[190:193], v[126:129]
	v_mfma_f32_16x16x32_bf16 v[122:125], v[162:165], v[190:193], v[122:125]
	v_mfma_f32_16x16x32_bf16 v[110:113], v[154:157], v[198:201], v[110:113]
	v_mfma_f32_16x16x32_bf16 v[106:109], v[162:165], v[198:201], v[106:109]
	v_mfma_f32_16x16x32_bf16 v[94:97], v[154:157], v[206:209], v[94:97]
	v_mfma_f32_16x16x32_bf16 v[90:93], v[162:165], v[206:209], v[90:93]
	v_mfma_f32_16x16x32_bf16 v[78:81], v[154:157], v[214:217], v[78:81]
	v_mfma_f32_16x16x32_bf16 v[74:77], v[162:165], v[214:217], v[74:77]
	v_mfma_f32_16x16x32_bf16 v[126:129], v[158:161], v[194:197], v[126:129]
	v_mfma_f32_16x16x32_bf16 v[122:125], v[166:169], v[194:197], v[122:125]
	v_mfma_f32_16x16x32_bf16 v[110:113], v[158:161], v[202:205], v[110:113]
	v_mfma_f32_16x16x32_bf16 v[106:109], v[166:169], v[202:205], v[106:109]
	v_mfma_f32_16x16x32_bf16 v[94:97], v[158:161], v[210:213], v[94:97]
	v_mfma_f32_16x16x32_bf16 v[90:93], v[166:169], v[210:213], v[90:93]
	v_mfma_f32_16x16x32_bf16 v[78:81], v[158:161], v[218:221], v[78:81]
	v_mfma_f32_16x16x32_bf16 v[74:77], v[166:169], v[218:221], v[74:77]
	s_setprio 0
	s_setprio 1
	v_mfma_f32_16x16x32_bf16 v[118:121], v[170:173], v[190:193], v[118:121]
	v_mfma_f32_16x16x32_bf16 v[114:117], v[182:185], v[190:193], v[114:117]
	v_mfma_f32_16x16x32_bf16 v[102:105], v[170:173], v[198:201], v[102:105]
	v_mfma_f32_16x16x32_bf16 v[98:101], v[182:185], v[198:201], v[98:101]
	v_mfma_f32_16x16x32_bf16 v[86:89], v[170:173], v[206:209], v[86:89]
	v_mfma_f32_16x16x32_bf16 v[82:85], v[182:185], v[206:209], v[82:85]
	v_mfma_f32_16x16x32_bf16 v[70:73], v[170:173], v[214:217], v[70:73]
	v_mfma_f32_16x16x32_bf16 v[66:69], v[182:185], v[214:217], v[66:69]
	v_mfma_f32_16x16x32_bf16 v[118:121], v[178:181], v[194:197], v[118:121]
	v_mfma_f32_16x16x32_bf16 v[114:117], v[186:189], v[194:197], v[114:117]
	v_mfma_f32_16x16x32_bf16 v[102:105], v[178:181], v[202:205], v[102:105]
	v_mfma_f32_16x16x32_bf16 v[98:101], v[186:189], v[202:205], v[98:101]
	v_mfma_f32_16x16x32_bf16 v[86:89], v[178:181], v[210:213], v[86:89]
	v_mfma_f32_16x16x32_bf16 v[82:85], v[186:189], v[210:213], v[82:85]
	v_mfma_f32_16x16x32_bf16 v[70:73], v[178:181], v[218:221], v[70:73]
	v_mfma_f32_16x16x32_bf16 v[66:69], v[186:189], v[218:221], v[66:69]
	s_setprio 0
	s_barrier
	s_add_i32 s64, s57, s45
	v_lshl_add_u64 v[174:175], s[38:39], 0, v[134:135]
	s_mov_b32 m0, s64
	ds_read_b128 v[190:193], v152 offset:16384
	ds_read_b128 v[194:197], v152 offset:17408
	ds_read_b128 v[198:201], v152 offset:18432
	ds_read_b128 v[202:205], v152 offset:19456
	ds_read_b128 v[206:209], v152 offset:20480
	ds_read_b128 v[210:213], v152 offset:21504
	ds_read_b128 v[214:217], v152 offset:22528
	ds_read_b128 v[218:221], v152 offset:23552
	global_load_lds_dwordx4 v[174:175], off
	s_add_i32 m0, s64, 0x2000
	s_add_u32 s64, s38, 0x80000
	v_lshl_add_u64 v[222:223], s[38:39], 0, v[130:131]
	s_addc_u32 s65, s39, 0
	s_add_i32 s66, s58, s45
	global_load_lds_dwordx4 v[222:223], off
	v_lshl_add_u64 v[224:225], s[64:65], 0, v[134:135]
	s_mov_b32 m0, s66
	v_lshl_add_u64 v[226:227], s[40:41], 0, v[132:133]
	global_load_lds_dwordx4 v[224:225], off
	v_lshl_add_u64 v[224:225], s[64:65], 0, v[130:131]
	s_add_i32 m0, s66, 0x2000
	s_nop 0
	global_load_lds_dwordx4 v[224:225], off
	v_lshl_add_u64 v[224:225], s[40:41], 0, v[136:137]
	s_mov_b32 m0, s25
	s_nop 0
	global_load_lds_dwordx4 v[224:225], off
	s_mov_b32 m0, s50
	s_nop 0
	global_load_lds_dwordx4 v[226:227], off
	s_waitcnt vmcnt(8)
	s_waitcnt lgkmcnt(0)
	s_barrier
	s_setprio 1
	s_waitcnt lgkmcnt(0)
	v_mfma_f32_16x16x32_bf16 v[62:65], v[154:157], v[190:193], v[62:65]
	v_mfma_f32_16x16x32_bf16 v[58:61], v[162:165], v[190:193], v[58:61]
	v_mfma_f32_16x16x32_bf16 v[46:49], v[154:157], v[198:201], v[46:49]
	v_mfma_f32_16x16x32_bf16 v[42:45], v[162:165], v[198:201], v[42:45]
	v_mfma_f32_16x16x32_bf16 v[30:33], v[154:157], v[206:209], v[30:33]
	v_mfma_f32_16x16x32_bf16 v[26:29], v[162:165], v[206:209], v[26:29]
	v_mfma_f32_16x16x32_bf16 v[14:17], v[154:157], v[214:217], v[14:17]
	v_mfma_f32_16x16x32_bf16 v[10:13], v[162:165], v[214:217], v[10:13]
	v_mfma_f32_16x16x32_bf16 v[62:65], v[158:161], v[194:197], v[62:65]
	v_mfma_f32_16x16x32_bf16 v[58:61], v[166:169], v[194:197], v[58:61]
	v_mfma_f32_16x16x32_bf16 v[46:49], v[158:161], v[202:205], v[46:49]
	v_mfma_f32_16x16x32_bf16 v[42:45], v[166:169], v[202:205], v[42:45]
	v_mfma_f32_16x16x32_bf16 v[30:33], v[158:161], v[210:213], v[30:33]
	v_mfma_f32_16x16x32_bf16 v[26:29], v[166:169], v[210:213], v[26:29]
	v_mfma_f32_16x16x32_bf16 v[14:17], v[158:161], v[218:221], v[14:17]
	v_mfma_f32_16x16x32_bf16 v[10:13], v[166:169], v[218:221], v[10:13]
	s_setprio 0
	s_setprio 1
	v_mfma_f32_16x16x32_bf16 v[54:57], v[170:173], v[190:193], v[54:57]
	v_mfma_f32_16x16x32_bf16 v[50:53], v[182:185], v[190:193], v[50:53]
	v_mfma_f32_16x16x32_bf16 v[38:41], v[170:173], v[198:201], v[38:41]
	v_mfma_f32_16x16x32_bf16 v[34:37], v[182:185], v[198:201], v[34:37]
	v_mfma_f32_16x16x32_bf16 v[22:25], v[170:173], v[206:209], v[22:25]
	v_mfma_f32_16x16x32_bf16 v[18:21], v[182:185], v[206:209], v[18:21]
	v_mfma_f32_16x16x32_bf16 v[6:9], v[170:173], v[214:217], v[6:9]
	v_mfma_f32_16x16x32_bf16 v[2:5], v[182:185], v[214:217], v[2:5]
	v_mfma_f32_16x16x32_bf16 v[54:57], v[178:181], v[194:197], v[54:57]
	v_mfma_f32_16x16x32_bf16 v[50:53], v[186:189], v[194:197], v[50:53]
	v_mfma_f32_16x16x32_bf16 v[38:41], v[178:181], v[202:205], v[38:41]
	v_mfma_f32_16x16x32_bf16 v[34:37], v[186:189], v[202:205], v[34:37]
	v_mfma_f32_16x16x32_bf16 v[22:25], v[178:181], v[210:213], v[22:25]
	v_mfma_f32_16x16x32_bf16 v[18:21], v[186:189], v[210:213], v[18:21]
	v_mfma_f32_16x16x32_bf16 v[6:9], v[178:181], v[218:221], v[6:9]
	v_mfma_f32_16x16x32_bf16 v[2:5], v[186:189], v[218:221], v[2:5]
	s_setprio 0
	s_barrier
	s_add_i32 s64, 0, 0x18000
	v_add_u32_e32 v153, s64, v148
	s_add_i32 s65, 0, 0x1c000
	ds_read_b128 v[154:157], v153
	ds_read_b128 v[158:161], v153 offset:1024
	ds_read_b128 v[162:165], v153 offset:2048
	ds_read_b128 v[166:169], v153 offset:3072
	v_add_u32_e32 v153, s65, v148
	ds_read_b128 v[170:173], v153
	ds_read_b128 v[178:181], v153 offset:1024
	ds_read_b128 v[182:185], v153 offset:2048
	ds_read_b128 v[186:189], v153 offset:3072
	s_add_u32 s40, s40, 0x80000
	s_addc_u32 s41, s41, 0
	s_mov_b32 m0, s51
	v_lshl_add_u64 v[228:229], s[40:41], 0, v[136:137]
	ds_read_b128 v[190:193], v152 offset:32768
	ds_read_b128 v[194:197], v152 offset:33792
	ds_read_b128 v[198:201], v152 offset:34816
	ds_read_b128 v[202:205], v152 offset:35840
	ds_read_b128 v[206:209], v152 offset:36864
	ds_read_b128 v[210:213], v152 offset:37888
	ds_read_b128 v[214:217], v152 offset:38912
	ds_read_b128 v[218:221], v152 offset:39936
	global_load_lds_dwordx4 v[228:229], off
	v_lshl_add_u64 v[228:229], s[40:41], 0, v[132:133]
	s_mov_b32 m0, s52
	s_nop 0
	global_load_lds_dwordx4 v[228:229], off
	s_waitcnt vmcnt(8)
	s_waitcnt lgkmcnt(0)
	s_barrier
	s_setprio 1
	s_waitcnt lgkmcnt(0)
	v_mfma_f32_16x16x32_bf16 v[126:129], v[154:157], v[190:193], v[126:129]
	v_mfma_f32_16x16x32_bf16 v[122:125], v[162:165], v[190:193], v[122:125]
	v_mfma_f32_16x16x32_bf16 v[110:113], v[154:157], v[198:201], v[110:113]
	v_mfma_f32_16x16x32_bf16 v[106:109], v[162:165], v[198:201], v[106:109]
	v_mfma_f32_16x16x32_bf16 v[94:97], v[154:157], v[206:209], v[94:97]
	v_mfma_f32_16x16x32_bf16 v[90:93], v[162:165], v[206:209], v[90:93]
	v_mfma_f32_16x16x32_bf16 v[78:81], v[154:157], v[214:217], v[78:81]
	v_mfma_f32_16x16x32_bf16 v[74:77], v[162:165], v[214:217], v[74:77]
	v_mfma_f32_16x16x32_bf16 v[126:129], v[158:161], v[194:197], v[126:129]
	v_mfma_f32_16x16x32_bf16 v[122:125], v[166:169], v[194:197], v[122:125]
	v_mfma_f32_16x16x32_bf16 v[110:113], v[158:161], v[202:205], v[110:113]
	v_mfma_f32_16x16x32_bf16 v[106:109], v[166:169], v[202:205], v[106:109]
	v_mfma_f32_16x16x32_bf16 v[94:97], v[158:161], v[210:213], v[94:97]
	v_mfma_f32_16x16x32_bf16 v[90:93], v[166:169], v[210:213], v[90:93]
	v_mfma_f32_16x16x32_bf16 v[78:81], v[158:161], v[218:221], v[78:81]
	v_mfma_f32_16x16x32_bf16 v[74:77], v[166:169], v[218:221], v[74:77]
	s_setprio 0
	s_setprio 1
	v_mfma_f32_16x16x32_bf16 v[118:121], v[170:173], v[190:193], v[118:121]
	v_mfma_f32_16x16x32_bf16 v[114:117], v[182:185], v[190:193], v[114:117]
	v_mfma_f32_16x16x32_bf16 v[102:105], v[170:173], v[198:201], v[102:105]
	v_mfma_f32_16x16x32_bf16 v[98:101], v[182:185], v[198:201], v[98:101]
	v_mfma_f32_16x16x32_bf16 v[86:89], v[170:173], v[206:209], v[86:89]
	v_mfma_f32_16x16x32_bf16 v[82:85], v[182:185], v[206:209], v[82:85]
	v_mfma_f32_16x16x32_bf16 v[70:73], v[170:173], v[214:217], v[70:73]
	v_mfma_f32_16x16x32_bf16 v[66:69], v[182:185], v[214:217], v[66:69]
	v_mfma_f32_16x16x32_bf16 v[118:121], v[178:181], v[194:197], v[118:121]
	v_mfma_f32_16x16x32_bf16 v[114:117], v[186:189], v[194:197], v[114:117]
	v_mfma_f32_16x16x32_bf16 v[102:105], v[178:181], v[202:205], v[102:105]
	v_mfma_f32_16x16x32_bf16 v[98:101], v[186:189], v[202:205], v[98:101]
	v_mfma_f32_16x16x32_bf16 v[86:89], v[178:181], v[210:213], v[86:89]
	v_mfma_f32_16x16x32_bf16 v[82:85], v[186:189], v[210:213], v[82:85]
	v_mfma_f32_16x16x32_bf16 v[70:73], v[178:181], v[218:221], v[70:73]
	v_mfma_f32_16x16x32_bf16 v[66:69], v[186:189], v[218:221], v[66:69]
	s_setprio 0
	s_barrier
	s_add_i32 s40, s64, s45
	v_lshl_add_u64 v[174:175], v[174:175], 0, s[8:9]
	s_mov_b32 m0, s40
	ds_read_b128 v[190:193], v152 offset:49152
	ds_read_b128 v[194:197], v152 offset:50176
	ds_read_b128 v[198:201], v152 offset:51200
	ds_read_b128 v[202:205], v152 offset:52224
	ds_read_b128 v[206:209], v152 offset:53248
	ds_read_b128 v[210:213], v152 offset:54272
	ds_read_b128 v[214:217], v152 offset:55296
	ds_read_b128 v[218:221], v152 offset:56320
	global_load_lds_dwordx4 v[174:175], off
	s_add_i32 m0, s40, 0x2000
	s_add_u32 s38, s38, 0x80080
	v_lshl_add_u64 v[174:175], v[222:223], 0, s[8:9]
	s_addc_u32 s39, s39, 0
	s_add_i32 s40, s65, s45
	global_load_lds_dwordx4 v[174:175], off
	v_lshl_add_u64 v[174:175], s[38:39], 0, v[134:135]
	s_mov_b32 m0, s40
	s_nop 0
	global_load_lds_dwordx4 v[174:175], off
	v_lshl_add_u64 v[174:175], s[38:39], 0, v[130:131]
	s_add_i32 m0, s40, 0x2000
	s_nop 0
	global_load_lds_dwordx4 v[174:175], off
	v_lshl_add_u64 v[174:175], v[224:225], 0, s[8:9]
	s_mov_b32 m0, s55
	s_nop 0
	global_load_lds_dwordx4 v[174:175], off
	v_lshl_add_u64 v[174:175], v[226:227], 0, s[8:9]
	s_mov_b32 m0, s56
	s_nop 0
	global_load_lds_dwordx4 v[174:175], off
	s_waitcnt vmcnt(8)
	s_waitcnt lgkmcnt(0)
	s_barrier
	s_setprio 1
	s_waitcnt lgkmcnt(0)
	v_mfma_f32_16x16x32_bf16 v[62:65], v[154:157], v[190:193], v[62:65]
	v_mfma_f32_16x16x32_bf16 v[58:61], v[162:165], v[190:193], v[58:61]
	v_mfma_f32_16x16x32_bf16 v[46:49], v[154:157], v[198:201], v[46:49]
	v_mfma_f32_16x16x32_bf16 v[42:45], v[162:165], v[198:201], v[42:45]
	v_mfma_f32_16x16x32_bf16 v[30:33], v[154:157], v[206:209], v[30:33]
	v_mfma_f32_16x16x32_bf16 v[26:29], v[162:165], v[206:209], v[26:29]
	v_mfma_f32_16x16x32_bf16 v[14:17], v[154:157], v[214:217], v[14:17]
	v_mfma_f32_16x16x32_bf16 v[10:13], v[162:165], v[214:217], v[10:13]
	v_mfma_f32_16x16x32_bf16 v[62:65], v[158:161], v[194:197], v[62:65]
	v_mfma_f32_16x16x32_bf16 v[58:61], v[166:169], v[194:197], v[58:61]
	v_mfma_f32_16x16x32_bf16 v[46:49], v[158:161], v[202:205], v[46:49]
	v_mfma_f32_16x16x32_bf16 v[42:45], v[166:169], v[202:205], v[42:45]
	v_mfma_f32_16x16x32_bf16 v[30:33], v[158:161], v[210:213], v[30:33]
	v_mfma_f32_16x16x32_bf16 v[26:29], v[166:169], v[210:213], v[26:29]
	v_mfma_f32_16x16x32_bf16 v[14:17], v[158:161], v[218:221], v[14:17]
	v_mfma_f32_16x16x32_bf16 v[10:13], v[166:169], v[218:221], v[10:13]
	s_setprio 0
	s_setprio 1
	v_mfma_f32_16x16x32_bf16 v[54:57], v[170:173], v[190:193], v[54:57]
	v_mfma_f32_16x16x32_bf16 v[50:53], v[182:185], v[190:193], v[50:53]
	v_mfma_f32_16x16x32_bf16 v[38:41], v[170:173], v[198:201], v[38:41]
	v_mfma_f32_16x16x32_bf16 v[34:37], v[182:185], v[198:201], v[34:37]
	v_mfma_f32_16x16x32_bf16 v[22:25], v[170:173], v[206:209], v[22:25]
	v_mfma_f32_16x16x32_bf16 v[18:21], v[182:185], v[206:209], v[18:21]
	v_mfma_f32_16x16x32_bf16 v[6:9], v[170:173], v[214:217], v[6:9]
	v_mfma_f32_16x16x32_bf16 v[2:5], v[182:185], v[214:217], v[2:5]
	v_mfma_f32_16x16x32_bf16 v[54:57], v[178:181], v[194:197], v[54:57]
	v_mfma_f32_16x16x32_bf16 v[50:53], v[186:189], v[194:197], v[50:53]
	v_mfma_f32_16x16x32_bf16 v[38:41], v[178:181], v[202:205], v[38:41]
	v_mfma_f32_16x16x32_bf16 v[34:37], v[186:189], v[202:205], v[34:37]
	v_mfma_f32_16x16x32_bf16 v[22:25], v[178:181], v[210:213], v[22:25]
	v_mfma_f32_16x16x32_bf16 v[18:21], v[186:189], v[210:213], v[18:21]
	v_mfma_f32_16x16x32_bf16 v[6:9], v[178:181], v[218:221], v[6:9]
	v_mfma_f32_16x16x32_bf16 v[2:5], v[186:189], v[218:221], v[2:5]
	s_setprio 0
	s_add_i32 s63, s63, 2
	s_add_u32 s36, s36, 0x100
	s_addc_u32 s37, s37, 0
	s_add_u32 s61, s61, 0x100
	s_addc_u32 s62, s62, 0
	s_cmp_gt_u32 s63, 29
	s_barrier
	s_cbranch_scc0 .LBB0_1043
	s_and_b64 vcc, exec, s[10:11]
	s_cbranch_vccz .LBB0_1046
	s_barrier

.LBB0_1138:
	ds_read_b128 v[142:145], v166
	ds_read_b128 v[148:151], v166 offset:1024
	ds_read_b128 v[152:155], v166 offset:2048
	ds_read_b128 v[156:159], v166 offset:3072
	ds_read_b128 v[160:163], v167
	ds_read_b128 v[172:175], v167 offset:1024
	ds_read_b128 v[178:181], v167 offset:2048
	ds_read_b128 v[182:185], v167 offset:3072
	s_add_u32 s24, s22, 0x100
	s_addc_u32 s25, s23, 0
	s_cmpk_eq_i32 s74, 0x54
	s_cselect_b32 s39, s5, s25
	s_cselect_b32 s38, s4, s24
	s_cselect_b32 s37, s21, s69
	s_cselect_b32 s36, s20, s67
	v_lshl_add_u64 v[218:219], s[22:23], 0, v[134:135]
	s_add_i32 m0, s45, 0xc000
	ds_read_b128 v[186:189], v168
	ds_read_b128 v[190:193], v168 offset:1024
	ds_read_b128 v[194:197], v168 offset:2048
	ds_read_b128 v[198:201], v168 offset:3072
	ds_read_b128 v[202:205], v168 offset:4096
	ds_read_b128 v[206:209], v168 offset:5120
	ds_read_b128 v[210:213], v168 offset:6144
	ds_read_b128 v[214:217], v168 offset:7168
	global_load_lds_dwordx4 v[218:219], off
	v_lshl_add_u64 v[218:219], s[22:23], 0, v[136:137]
	s_add_i32 m0, s45, 0xe000
	s_nop 0
	global_load_lds_dwordx4 v[218:219], off
	s_waitcnt vmcnt(8)
	s_waitcnt lgkmcnt(0)
	s_barrier
	s_setprio 1
	s_waitcnt lgkmcnt(0)
	v_mfma_f32_16x16x32_bf16 v[122:125], v[142:145], v[186:189], v[122:125]
	v_mfma_f32_16x16x32_bf16 v[126:129], v[152:155], v[186:189], v[126:129]
	v_mfma_f32_16x16x32_bf16 v[114:117], v[142:145], v[194:197], v[114:117]
	v_mfma_f32_16x16x32_bf16 v[118:121], v[152:155], v[194:197], v[118:121]
	v_mfma_f32_16x16x32_bf16 v[94:97], v[142:145], v[202:205], v[94:97]
	v_mfma_f32_16x16x32_bf16 v[90:93], v[152:155], v[202:205], v[90:93]
	v_mfma_f32_16x16x32_bf16 v[86:89], v[142:145], v[210:213], v[86:89]
	v_mfma_f32_16x16x32_bf16 v[82:85], v[152:155], v[210:213], v[82:85]
	v_mfma_f32_16x16x32_bf16 v[122:125], v[148:151], v[190:193], v[122:125]
	v_mfma_f32_16x16x32_bf16 v[126:129], v[156:159], v[190:193], v[126:129]
	v_mfma_f32_16x16x32_bf16 v[114:117], v[148:151], v[198:201], v[114:117]
	v_mfma_f32_16x16x32_bf16 v[118:121], v[156:159], v[198:201], v[118:121]
	v_mfma_f32_16x16x32_bf16 v[94:97], v[148:151], v[206:209], v[94:97]
	v_mfma_f32_16x16x32_bf16 v[90:93], v[156:159], v[206:209], v[90:93]
	v_mfma_f32_16x16x32_bf16 v[86:89], v[148:151], v[214:217], v[86:89]
	v_mfma_f32_16x16x32_bf16 v[82:85], v[156:159], v[214:217], v[82:85]
	s_setprio 0
	s_setprio 1
	v_mfma_f32_16x16x32_bf16 v[110:113], v[160:163], v[186:189], v[110:113]
	v_mfma_f32_16x16x32_bf16 v[106:109], v[178:181], v[186:189], v[106:109]
	v_mfma_f32_16x16x32_bf16 v[102:105], v[160:163], v[194:197], v[102:105]
	v_mfma_f32_16x16x32_bf16 v[98:101], v[178:181], v[194:197], v[98:101]
	v_mfma_f32_16x16x32_bf16 v[78:81], v[160:163], v[202:205], v[78:81]
	v_mfma_f32_16x16x32_bf16 v[74:77], v[178:181], v[202:205], v[74:77]
	v_mfma_f32_16x16x32_bf16 v[70:73], v[160:163], v[210:213], v[70:73]
	v_mfma_f32_16x16x32_bf16 v[66:69], v[178:181], v[210:213], v[66:69]
	v_mfma_f32_16x16x32_bf16 v[110:113], v[172:175], v[190:193], v[110:113]
	v_mfma_f32_16x16x32_bf16 v[106:109], v[182:185], v[190:193], v[106:109]
	v_mfma_f32_16x16x32_bf16 v[102:105], v[172:175], v[198:201], v[102:105]
	v_mfma_f32_16x16x32_bf16 v[98:101], v[182:185], v[198:201], v[98:101]
	v_mfma_f32_16x16x32_bf16 v[78:81], v[172:175], v[206:209], v[78:81]
	v_mfma_f32_16x16x32_bf16 v[74:77], v[182:185], v[206:209], v[74:77]
	v_mfma_f32_16x16x32_bf16 v[70:73], v[172:175], v[214:217], v[70:73]
	v_mfma_f32_16x16x32_bf16 v[66:69], v[182:185], v[214:217], v[66:69]
	s_setprio 0
	s_barrier
	s_add_i32 s22, s46, s44
	v_lshl_add_u64 v[218:219], s[36:37], 0, v[130:131]
	s_mov_b32 m0, s22
	ds_read_b128 v[186:189], v168 offset:16384
	ds_read_b128 v[190:193], v168 offset:17408
	ds_read_b128 v[194:197], v168 offset:18432
	ds_read_b128 v[198:201], v168 offset:19456
	ds_read_b128 v[202:205], v168 offset:20480
	ds_read_b128 v[206:209], v168 offset:21504
	ds_read_b128 v[210:213], v168 offset:22528
	ds_read_b128 v[214:217], v168 offset:23552
	global_load_lds_dwordx4 v[218:219], off
	s_add_i32 m0, s22, 0x2000
	s_add_u32 s22, s36, 0x160000
	v_lshl_add_u64 v[220:221], s[36:37], 0, v[132:133]
	s_addc_u32 s23, s37, 0
	s_add_i32 s72, s47, s44
	global_load_lds_dwordx4 v[220:221], off
	v_lshl_add_u64 v[222:223], s[22:23], 0, v[130:131]
	s_mov_b32 m0, s72
	v_lshl_add_u64 v[224:225], s[38:39], 0, v[132:133]
	global_load_lds_dwordx4 v[222:223], off
	v_lshl_add_u64 v[222:223], s[22:23], 0, v[132:133]
	s_add_i32 m0, s72, 0x2000
	s_nop 0
	global_load_lds_dwordx4 v[222:223], off
	v_lshl_add_u64 v[222:223], s[38:39], 0, v[130:131]
	s_mov_b32 m0, s45
	s_nop 0
	global_load_lds_dwordx4 v[222:223], off
	s_mov_b32 m0, s48
	s_nop 0
	global_load_lds_dwordx4 v[224:225], off
	s_waitcnt vmcnt(8)
	s_waitcnt lgkmcnt(0)
	s_barrier
	s_setprio 1
	s_waitcnt lgkmcnt(0)
	v_mfma_f32_16x16x32_bf16 v[62:65], v[142:145], v[186:189], v[62:65]
	v_mfma_f32_16x16x32_bf16 v[58:61], v[152:155], v[186:189], v[58:61]
	v_mfma_f32_16x16x32_bf16 v[54:57], v[142:145], v[194:197], v[54:57]
	v_mfma_f32_16x16x32_bf16 v[50:53], v[152:155], v[194:197], v[50:53]
	v_mfma_f32_16x16x32_bf16 v[30:33], v[142:145], v[202:205], v[30:33]
	v_mfma_f32_16x16x32_bf16 v[26:29], v[152:155], v[202:205], v[26:29]
	v_mfma_f32_16x16x32_bf16 v[22:25], v[142:145], v[210:213], v[22:25]
	v_mfma_f32_16x16x32_bf16 v[18:21], v[152:155], v[210:213], v[18:21]
	v_mfma_f32_16x16x32_bf16 v[62:65], v[148:151], v[190:193], v[62:65]
	v_mfma_f32_16x16x32_bf16 v[58:61], v[156:159], v[190:193], v[58:61]
	v_mfma_f32_16x16x32_bf16 v[54:57], v[148:151], v[198:201], v[54:57]
	v_mfma_f32_16x16x32_bf16 v[50:53], v[156:159], v[198:201], v[50:53]
	v_mfma_f32_16x16x32_bf16 v[30:33], v[148:151], v[206:209], v[30:33]
	v_mfma_f32_16x16x32_bf16 v[26:29], v[156:159], v[206:209], v[26:29]
	v_mfma_f32_16x16x32_bf16 v[22:25], v[148:151], v[214:217], v[22:25]
	v_mfma_f32_16x16x32_bf16 v[18:21], v[156:159], v[214:217], v[18:21]
	s_setprio 0
	s_setprio 1
	v_mfma_f32_16x16x32_bf16 v[46:49], v[160:163], v[186:189], v[46:49]
	v_mfma_f32_16x16x32_bf16 v[42:45], v[178:181], v[186:189], v[42:45]
	v_mfma_f32_16x16x32_bf16 v[38:41], v[160:163], v[194:197], v[38:41]
	v_mfma_f32_16x16x32_bf16 v[34:37], v[178:181], v[194:197], v[34:37]
	v_mfma_f32_16x16x32_bf16 v[14:17], v[160:163], v[202:205], v[14:17]
	v_mfma_f32_16x16x32_bf16 v[10:13], v[178:181], v[202:205], v[10:13]
	v_mfma_f32_16x16x32_bf16 v[6:9], v[160:163], v[210:213], v[6:9]
	v_mfma_f32_16x16x32_bf16 v[2:5], v[178:181], v[210:213], v[2:5]
	v_mfma_f32_16x16x32_bf16 v[46:49], v[172:175], v[190:193], v[46:49]
	v_mfma_f32_16x16x32_bf16 v[42:45], v[182:185], v[190:193], v[42:45]
	v_mfma_f32_16x16x32_bf16 v[38:41], v[172:175], v[198:201], v[38:41]
	v_mfma_f32_16x16x32_bf16 v[34:37], v[182:185], v[198:201], v[34:37]
	v_mfma_f32_16x16x32_bf16 v[14:17], v[172:175], v[206:209], v[14:17]
	v_mfma_f32_16x16x32_bf16 v[10:13], v[182:185], v[206:209], v[10:13]
	v_mfma_f32_16x16x32_bf16 v[6:9], v[172:175], v[214:217], v[6:9]
	v_mfma_f32_16x16x32_bf16 v[2:5], v[182:185], v[214:217], v[2:5]
	s_setprio 0
	s_barrier
	s_add_i32 s72, 0, 0x18000
	s_add_i32 s73, 0, 0x1c000
	v_add_u32_e32 v156, s72, v164
	v_add_u32_e32 v171, s73, v164
	ds_read_b128 v[142:145], v156
	ds_read_b128 v[148:151], v156 offset:1024
	ds_read_b128 v[152:155], v156 offset:2048
	ds_read_b128 v[156:159], v156 offset:3072
	ds_read_b128 v[160:163], v171
	ds_read_b128 v[172:175], v171 offset:1024
	ds_read_b128 v[178:181], v171 offset:2048
	ds_read_b128 v[182:185], v171 offset:3072
	s_add_u32 s22, s38, 0x160000
	s_addc_u32 s23, s39, 0
	s_mov_b32 m0, s49
	v_lshl_add_u64 v[226:227], s[22:23], 0, v[130:131]
	ds_read_b128 v[186:189], v168 offset:32768
	ds_read_b128 v[190:193], v168 offset:33792
	ds_read_b128 v[194:197], v168 offset:34816
	ds_read_b128 v[198:201], v168 offset:35840
	ds_read_b128 v[202:205], v168 offset:36864
	ds_read_b128 v[206:209], v168 offset:37888
	ds_read_b128 v[210:213], v168 offset:38912
	ds_read_b128 v[214:217], v168 offset:39936
	global_load_lds_dwordx4 v[226:227], off
	v_lshl_add_u64 v[226:227], s[22:23], 0, v[132:133]
	s_mov_b32 m0, s50
	s_nop 0
	global_load_lds_dwordx4 v[226:227], off
	s_waitcnt vmcnt(8)
	s_waitcnt lgkmcnt(0)
	s_barrier
	s_setprio 1
	s_waitcnt lgkmcnt(0)
	v_mfma_f32_16x16x32_bf16 v[122:125], v[142:145], v[186:189], v[122:125]
	v_mfma_f32_16x16x32_bf16 v[126:129], v[152:155], v[186:189], v[126:129]
	v_mfma_f32_16x16x32_bf16 v[114:117], v[142:145], v[194:197], v[114:117]
	v_mfma_f32_16x16x32_bf16 v[118:121], v[152:155], v[194:197], v[118:121]
	v_mfma_f32_16x16x32_bf16 v[94:97], v[142:145], v[202:205], v[94:97]
	v_mfma_f32_16x16x32_bf16 v[90:93], v[152:155], v[202:205], v[90:93]
	v_mfma_f32_16x16x32_bf16 v[86:89], v[142:145], v[210:213], v[86:89]
	v_mfma_f32_16x16x32_bf16 v[82:85], v[152:155], v[210:213], v[82:85]
	v_mfma_f32_16x16x32_bf16 v[122:125], v[148:151], v[190:193], v[122:125]
	v_mfma_f32_16x16x32_bf16 v[126:129], v[156:159], v[190:193], v[126:129]
	v_mfma_f32_16x16x32_bf16 v[114:117], v[148:151], v[198:201], v[114:117]
	v_mfma_f32_16x16x32_bf16 v[118:121], v[156:159], v[198:201], v[118:121]
	v_mfma_f32_16x16x32_bf16 v[94:97], v[148:151], v[206:209], v[94:97]
	v_mfma_f32_16x16x32_bf16 v[90:93], v[156:159], v[206:209], v[90:93]
	v_mfma_f32_16x16x32_bf16 v[86:89], v[148:151], v[214:217], v[86:89]
	v_mfma_f32_16x16x32_bf16 v[82:85], v[156:159], v[214:217], v[82:85]
	s_setprio 0
	s_setprio 1
	v_mfma_f32_16x16x32_bf16 v[110:113], v[160:163], v[186:189], v[110:113]
	v_mfma_f32_16x16x32_bf16 v[106:109], v[178:181], v[186:189], v[106:109]
	v_mfma_f32_16x16x32_bf16 v[102:105], v[160:163], v[194:197], v[102:105]
	v_mfma_f32_16x16x32_bf16 v[98:101], v[178:181], v[194:197], v[98:101]
	v_mfma_f32_16x16x32_bf16 v[78:81], v[160:163], v[202:205], v[78:81]
	v_mfma_f32_16x16x32_bf16 v[74:77], v[178:181], v[202:205], v[74:77]
	v_mfma_f32_16x16x32_bf16 v[70:73], v[160:163], v[210:213], v[70:73]
	v_mfma_f32_16x16x32_bf16 v[66:69], v[178:181], v[210:213], v[66:69]
	v_mfma_f32_16x16x32_bf16 v[110:113], v[172:175], v[190:193], v[110:113]
	v_mfma_f32_16x16x32_bf16 v[106:109], v[182:185], v[190:193], v[106:109]
	v_mfma_f32_16x16x32_bf16 v[102:105], v[172:175], v[198:201], v[102:105]
	v_mfma_f32_16x16x32_bf16 v[98:101], v[182:185], v[198:201], v[98:101]
	v_mfma_f32_16x16x32_bf16 v[78:81], v[172:175], v[206:209], v[78:81]
	v_mfma_f32_16x16x32_bf16 v[74:77], v[182:185], v[206:209], v[74:77]
	v_mfma_f32_16x16x32_bf16 v[70:73], v[172:175], v[214:217], v[70:73]
	v_mfma_f32_16x16x32_bf16 v[66:69], v[182:185], v[214:217], v[66:69]
	s_setprio 0
	s_barrier
	s_add_i32 s22, s72, s44
	v_lshl_add_u64 v[218:219], v[218:219], 0, s[8:9]
	s_mov_b32 m0, s22
	ds_read_b128 v[186:189], v168 offset:49152
	ds_read_b128 v[190:193], v168 offset:50176
	ds_read_b128 v[194:197], v168 offset:51200
	ds_read_b128 v[198:201], v168 offset:52224
	ds_read_b128 v[202:205], v168 offset:53248
	ds_read_b128 v[206:209], v168 offset:54272
	ds_read_b128 v[210:213], v168 offset:55296
	ds_read_b128 v[214:217], v168 offset:56320
	global_load_lds_dwordx4 v[218:219], off
	s_add_i32 m0, s22, 0x2000
	s_add_u32 s22, s36, 0x160080
	v_lshl_add_u64 v[218:219], v[220:221], 0, s[8:9]
	s_addc_u32 s23, s37, 0
	s_add_i32 s36, s73, s44
	global_load_lds_dwordx4 v[218:219], off
	v_lshl_add_u64 v[218:219], s[22:23], 0, v[130:131]
	s_mov_b32 m0, s36
	s_nop 0
	global_load_lds_dwordx4 v[218:219], off
	v_lshl_add_u64 v[218:219], s[22:23], 0, v[132:133]
	s_add_i32 m0, s36, 0x2000
	s_nop 0
	global_load_lds_dwordx4 v[218:219], off
	v_lshl_add_u64 v[218:219], v[222:223], 0, s[8:9]
	s_mov_b32 m0, s52
	s_nop 0
	global_load_lds_dwordx4 v[218:219], off
	v_lshl_add_u64 v[218:219], v[224:225], 0, s[8:9]
	s_mov_b32 m0, s53
	s_nop 0
	global_load_lds_dwordx4 v[218:219], off
	s_waitcnt vmcnt(8)
	s_waitcnt lgkmcnt(0)
	s_barrier
	s_setprio 1
	s_waitcnt lgkmcnt(0)
	v_mfma_f32_16x16x32_bf16 v[62:65], v[142:145], v[186:189], v[62:65]
	v_mfma_f32_16x16x32_bf16 v[58:61], v[152:155], v[186:189], v[58:61]
	v_mfma_f32_16x16x32_bf16 v[54:57], v[142:145], v[194:197], v[54:57]
	v_mfma_f32_16x16x32_bf16 v[50:53], v[152:155], v[194:197], v[50:53]
	v_mfma_f32_16x16x32_bf16 v[30:33], v[142:145], v[202:205], v[30:33]
	v_mfma_f32_16x16x32_bf16 v[26:29], v[152:155], v[202:205], v[26:29]
	v_mfma_f32_16x16x32_bf16 v[22:25], v[142:145], v[210:213], v[22:25]
	v_mfma_f32_16x16x32_bf16 v[18:21], v[152:155], v[210:213], v[18:21]
	v_mfma_f32_16x16x32_bf16 v[62:65], v[148:151], v[190:193], v[62:65]
	v_mfma_f32_16x16x32_bf16 v[58:61], v[156:159], v[190:193], v[58:61]
	v_mfma_f32_16x16x32_bf16 v[54:57], v[148:151], v[198:201], v[54:57]
	v_mfma_f32_16x16x32_bf16 v[50:53], v[156:159], v[198:201], v[50:53]
	v_mfma_f32_16x16x32_bf16 v[30:33], v[148:151], v[206:209], v[30:33]
	v_mfma_f32_16x16x32_bf16 v[26:29], v[156:159], v[206:209], v[26:29]
	v_mfma_f32_16x16x32_bf16 v[22:25], v[148:151], v[214:217], v[22:25]
	v_mfma_f32_16x16x32_bf16 v[18:21], v[156:159], v[214:217], v[18:21]
	s_setprio 0
	s_setprio 1
	v_mfma_f32_16x16x32_bf16 v[46:49], v[160:163], v[186:189], v[46:49]
	v_mfma_f32_16x16x32_bf16 v[42:45], v[178:181], v[186:189], v[42:45]
	v_mfma_f32_16x16x32_bf16 v[38:41], v[160:163], v[194:197], v[38:41]
	v_mfma_f32_16x16x32_bf16 v[34:37], v[178:181], v[194:197], v[34:37]
	v_mfma_f32_16x16x32_bf16 v[14:17], v[160:163], v[202:205], v[14:17]
	v_mfma_f32_16x16x32_bf16 v[10:13], v[178:181], v[202:205], v[10:13]
	v_mfma_f32_16x16x32_bf16 v[6:9], v[160:163], v[210:213], v[6:9]
	v_mfma_f32_16x16x32_bf16 v[2:5], v[178:181], v[210:213], v[2:5]
	v_mfma_f32_16x16x32_bf16 v[46:49], v[172:175], v[190:193], v[46:49]
	v_mfma_f32_16x16x32_bf16 v[42:45], v[182:185], v[190:193], v[42:45]
	v_mfma_f32_16x16x32_bf16 v[38:41], v[172:175], v[198:201], v[38:41]
	v_mfma_f32_16x16x32_bf16 v[34:37], v[182:185], v[198:201], v[34:37]
	v_mfma_f32_16x16x32_bf16 v[14:17], v[172:175], v[206:209], v[14:17]
	v_mfma_f32_16x16x32_bf16 v[10:13], v[182:185], v[206:209], v[10:13]
	v_mfma_f32_16x16x32_bf16 v[6:9], v[172:175], v[214:217], v[6:9]
	v_mfma_f32_16x16x32_bf16 v[2:5], v[182:185], v[214:217], v[2:5]
	s_setprio 0
	s_add_i32 s74, s74, 2
	s_add_u32 s67, s67, 0x100
	s_addc_u32 s69, s69, 0
	s_cmpk_gt_u32 s74, 0x55
	s_mov_b64 s[22:23], s[24:25]
	s_barrier
	s_cbranch_scc0 .LBB0_1138
	s_and_b64 vcc, exec, s[10:11]
	s_cbranch_vccz .LBB0_1141
	s_barrier
